# v31 + carry_scan (batched LDS reads in carry scan) + rope_pf (rope table loads prefetched one step ahead, counted vmcnt) + flat_top (XCD-last leader no longer waits for TOP add return)
# speedup vs baseline: 1.0306x; 1.0036x over previous
; __device__ __forceinline__ unsigned xb_ld(unsigned* p)              { return __hip_atomic_load(p, __ATOMIC_RELAXED, __HIP_MEMORY_SCOPE_AGENT); }
; __device__ __forceinline__ unsigned xb_add(unsigned* p, unsigned v) { return __hip_atomic_fetch_add(p, v, __ATOMIC_RELAXED, __HIP_MEMORY_SCOPE_AGENT); }
; #define XB_SPIN(cond, bar) do { unsigned _sp = 0; while (cond) { __builtin_amdgcn_s_sleep(1); \
;     if ((++_sp & 255u) == 0u) { if (xb_ld(&(bar)[XB_TMO])) break; if (_sp > XB_SPIN_CAP) { atomicAdd(&(bar)[XB_TMO], 1u); break; } } } } while (0)
; __device__ __forceinline__ void xcd_barrier(const XcdBarrier& b) {
;     ...
;         const unsigned old = xb_add(&bar[XB_XSUB(b.x)], 1u);
;         const unsigned gen = old / nloc;
;         if (old + 1u == (gen + 1u) * nloc) {
;             __builtin_amdgcn_fence(__ATOMIC_RELEASE, "agent");
;             asm volatile("s_waitcnt vmcnt(0)" ::: "memory");
;             const unsigned og = xb_add(&bar[XB_TOP], 1u);
;             const unsigned tg = og / nx;
;             if (og + 1u == (tg + 1u) * nx) xb_add(&bar[XB_TOPGEN], 1u);
;             else XB_SPIN(xb_ld(&bar[XB_TOPGEN]) == tg, bar);
;             __builtin_amdgcn_fence(__ATOMIC_ACQUIRE, "agent");
;             xb_add(&bar[XB_XGEN(b.x)], 1u);
;             asm volatile("s_waitcnt vmcnt(0)" ::: "memory");
;         } else {
;             XB_SPIN(xb_ld(&bar[XB_XGEN(b.x)]) == gen, bar);
;             __builtin_amdgcn_fence(__ATOMIC_ACQUIRE, "agent");
;             asm volatile("s_waitcnt vmcnt(0)" ::: "memory");
.LBB0_29:
	s_or_b64 exec, exec, s[12:13]
	v_cvt_f32_u32_e32 v4, v2
	s_waitcnt vmcnt(1)
	v_readfirstlane_b32 s0, v3
	v_sub_u32_e32 v3, 0, v2
	v_rcp_iflag_f32_e32 v4, v4
	v_add_u32_e32 v5, s0, v1
	v_mul_f32_e32 v4, 0x4f7ffffe, v4
	v_cvt_u32_f32_e32 v4, v4
	v_mul_lo_u32 v1, v3, v4
	v_mul_hi_u32 v1, v4, v1
	v_add_u32_e32 v1, v4, v1
	v_mul_hi_u32 v1, v5, v1
	v_mul_lo_u32 v3, v1, v2
	v_sub_u32_e32 v3, v5, v3
	v_add_u32_e32 v4, 1, v1
	v_cmp_ge_u32_e32 vcc, v3, v2
	s_nop 1
	v_cndmask_b32_e32 v1, v1, v4, vcc
	v_sub_u32_e32 v4, v3, v2
	v_cndmask_b32_e32 v3, v3, v4, vcc
	v_add_u32_e32 v4, 1, v1
	v_cmp_ge_u32_e32 vcc, v3, v2
	v_add_u32_e32 v3, 1, v5
	s_nop 0
	v_cndmask_b32_e32 v1, v1, v4, vcc
	v_mul_lo_u32 v4, v2, v1
	v_add_u32_e32 v2, v4, v2
	v_cmp_ne_u32_e32 vcc, v3, v2
	s_cbranch_vccnz .Lft_poll_0
	s_mov_b32 s0, 0xd96c8
	s_bitcmp1_b32 s0, s72
	s_cbranch_scc1 .Lft_nowb_0
	buffer_wbl2 sc1
.Lft_nowb_0:
	s_waitcnt vmcnt(0) lgkmcnt(0)
	v_readlane_b32 s0, v253, 12
	v_readlane_b32 s1, v253, 13
	v_mov_b32_e32 v4, 1
	s_nop 4
	global_atomic_add v33, v4, s[0:1]
.Lft_poll_0:
	s_waitcnt lgkmcnt(0)
	v_add_u32_e32 v1, 1, v1
	v_mul_lo_u32 v1, v1, v0
	s_mov_b64 vcc, exec
	s_and_saveexec_b64 s[0:1], vcc
	s_xor_b64 s[12:13], exec, s[0:1]
	s_cbranch_execz .LBB0_43
	v_readlane_b32 s0, v253, 12
	v_readlane_b32 s1, v253, 13
	s_waitcnt lgkmcnt(0)
	s_nop 3
	global_load_dword v0, v33, s[0:1] sc1
	s_waitcnt vmcnt(0)
	v_cmp_lt_u32_e32 vcc, v0, v1
	s_and_saveexec_b64 s[14:15], vcc
	s_cbranch_execz .LBB0_42
	s_mov_b32 s0, 1
	s_mov_b64 s[16:17], 0
	s_branch .LBB0_33

; __device__ __forceinline__ unsigned xb_ld(unsigned* p)              { return __hip_atomic_load(p, __ATOMIC_RELAXED, __HIP_MEMORY_SCOPE_AGENT); }
; __device__ __forceinline__ unsigned xb_add(unsigned* p, unsigned v) { return __hip_atomic_fetch_add(p, v, __ATOMIC_RELAXED, __HIP_MEMORY_SCOPE_AGENT); }
; #define XB_SPIN(cond, bar) do { unsigned _sp = 0; while (cond) { __builtin_amdgcn_s_sleep(1); \
;     if ((++_sp & 255u) == 0u) { if (xb_ld(&(bar)[XB_TMO])) break; if (_sp > XB_SPIN_CAP) { atomicAdd(&(bar)[XB_TMO], 1u); break; } } } } while (0)
; __device__ __forceinline__ void xcd_barrier(const XcdBarrier& b) {
;     ...
;             else XB_SPIN(xb_ld(&bar[XB_TOPGEN]) == tg, bar);
;             __builtin_amdgcn_fence(__ATOMIC_ACQUIRE, "agent");
;             xb_add(&bar[XB_XGEN(b.x)], 1u);
;             asm volatile("s_waitcnt vmcnt(0)" ::: "memory");
;         } else {
;             XB_SPIN(xb_ld(&bar[XB_XGEN(b.x)]) == gen, bar);
.LBB0_35:
	v_readlane_b32 s20, v253, 12
	v_readlane_b32 s21, v253, 13
	s_add_i32 s0, s0, 1
	s_mov_b64 s[22:23], -1
	s_nop 2
	global_load_dword v0, v33, s[20:21] sc1
	s_waitcnt vmcnt(0)
	v_cmp_ge_u32_e32 vcc, v0, v1
	s_orn2_b64 s[20:21], vcc, exec
	s_branch .LBB0_32

; __device__ __forceinline__ unsigned xb_ld(unsigned* p)              { return __hip_atomic_load(p, __ATOMIC_RELAXED, __HIP_MEMORY_SCOPE_AGENT); }
; __device__ __forceinline__ unsigned xb_add(unsigned* p, unsigned v) { return __hip_atomic_fetch_add(p, v, __ATOMIC_RELAXED, __HIP_MEMORY_SCOPE_AGENT); }
; #define XB_SPIN(cond, bar) do { unsigned _sp = 0; while (cond) { __builtin_amdgcn_s_sleep(1); \
;     if ((++_sp & 255u) == 0u) { if (xb_ld(&(bar)[XB_TMO])) break; if (_sp > XB_SPIN_CAP) { atomicAdd(&(bar)[XB_TMO], 1u); break; } } } } while (0)
; __device__ __forceinline__ void xcd_barrier(const XcdBarrier& b) {
;     ...
;         if (old + 1u == (gen + 1u) * nloc) {
;             __builtin_amdgcn_fence(__ATOMIC_RELEASE, "agent");
;             asm volatile("s_waitcnt vmcnt(0)" ::: "memory");
;             const unsigned og = xb_add(&bar[XB_TOP], 1u);
;             const unsigned tg = og / nx;
;             if (og + 1u == (tg + 1u) * nx) xb_add(&bar[XB_TOPGEN], 1u);
;             else XB_SPIN(xb_ld(&bar[XB_TOPGEN]) == tg, bar);
;             __builtin_amdgcn_fence(__ATOMIC_ACQUIRE, "agent");
;             xb_add(&bar[XB_XGEN(b.x)], 1u);
;             asm volatile("s_waitcnt vmcnt(0)" ::: "memory");
;         } else {
;             XB_SPIN(xb_ld(&bar[XB_XGEN(b.x)]) == gen, bar);
;             __builtin_amdgcn_fence(__ATOMIC_ACQUIRE, "agent");
;             asm volatile("s_waitcnt vmcnt(0)" ::: "memory");
;         }
;     }
;     __syncthreads();
.LBB0_43:
.LBB0_63:
	s_or_b64 exec, exec, s[4:5]
	s_mov_b64 s[4:5], 0
	s_waitcnt lgkmcnt(0)
	s_barrier

; __device__ __forceinline__ unsigned xb_ld(unsigned* p)              { return __hip_atomic_load(p, __ATOMIC_RELAXED, __HIP_MEMORY_SCOPE_AGENT); }
; __device__ __forceinline__ unsigned xb_add(unsigned* p, unsigned v) { return __hip_atomic_fetch_add(p, v, __ATOMIC_RELAXED, __HIP_MEMORY_SCOPE_AGENT); }
; #define XB_SPIN(cond, bar) do { unsigned _sp = 0; while (cond) { __builtin_amdgcn_s_sleep(1); \
;     if ((++_sp & 255u) == 0u) { if (xb_ld(&(bar)[XB_TMO])) break; if (_sp > XB_SPIN_CAP) { atomicAdd(&(bar)[XB_TMO], 1u); break; } } } } while (0)
; __device__ __forceinline__ void xcd_barrier(const XcdBarrier& b) {
;     ...
;         const unsigned old = xb_add(&bar[XB_XSUB(b.x)], 1u);
;         const unsigned gen = old / nloc;
;         if (old + 1u == (gen + 1u) * nloc) {
;             __builtin_amdgcn_fence(__ATOMIC_RELEASE, "agent");
;             asm volatile("s_waitcnt vmcnt(0)" ::: "memory");
;             const unsigned og = xb_add(&bar[XB_TOP], 1u);
;             const unsigned tg = og / nx;
;             if (og + 1u == (tg + 1u) * nx) xb_add(&bar[XB_TOPGEN], 1u);
;             else XB_SPIN(xb_ld(&bar[XB_TOPGEN]) == tg, bar);
;             __builtin_amdgcn_fence(__ATOMIC_ACQUIRE, "agent");
;             xb_add(&bar[XB_XGEN(b.x)], 1u);
;             asm volatile("s_waitcnt vmcnt(0)" ::: "memory");
;         } else {
;             XB_SPIN(xb_ld(&bar[XB_XGEN(b.x)]) == gen, bar);
;             __builtin_amdgcn_fence(__ATOMIC_ACQUIRE, "agent");
;             asm volatile("s_waitcnt vmcnt(0)" ::: "memory");
.LBB0_276:
	s_or_b64 exec, exec, s[18:19]
	v_cvt_f32_u32_e32 v4, v2
	s_waitcnt vmcnt(1)
	v_readfirstlane_b32 s0, v3
	v_sub_u32_e32 v3, 0, v2
	v_rcp_iflag_f32_e32 v4, v4
	v_add_u32_e32 v5, s0, v1
	v_mul_f32_e32 v4, 0x4f7ffffe, v4
	v_cvt_u32_f32_e32 v4, v4
	v_mul_lo_u32 v1, v3, v4
	v_mul_hi_u32 v1, v4, v1
	v_add_u32_e32 v1, v4, v1
	v_mul_hi_u32 v1, v5, v1
	v_mul_lo_u32 v3, v1, v2
	v_sub_u32_e32 v3, v5, v3
	v_add_u32_e32 v4, 1, v1
	v_cmp_ge_u32_e32 vcc, v3, v2
	s_nop 1
	v_cndmask_b32_e32 v1, v1, v4, vcc
	v_sub_u32_e32 v4, v3, v2
	v_cndmask_b32_e32 v3, v3, v4, vcc
	v_add_u32_e32 v4, 1, v1
	v_cmp_ge_u32_e32 vcc, v3, v2
	v_add_u32_e32 v3, 1, v5
	s_nop 0
	v_cndmask_b32_e32 v1, v1, v4, vcc
	v_mul_lo_u32 v4, v2, v1
	v_add_u32_e32 v2, v4, v2
	v_cmp_ne_u32_e32 vcc, v3, v2
	s_cbranch_vccnz .Lft_poll_1
	buffer_wbl2 sc1
	s_waitcnt vmcnt(0) lgkmcnt(0)
	v_readlane_b32 s0, v253, 12
	v_readlane_b32 s1, v253, 13
	v_mov_b32_e32 v4, 1
	s_nop 4
	global_atomic_add v33, v4, s[0:1]
.Lft_poll_1:
	s_waitcnt lgkmcnt(0)
	v_add_u32_e32 v1, 1, v1
	v_mul_lo_u32 v1, v1, v0
	s_mov_b64 vcc, exec
	s_and_saveexec_b64 s[0:1], vcc
	s_xor_b64 s[20:21], exec, s[0:1]
	s_cbranch_execz .LBB0_290
	v_readlane_b32 s0, v253, 12
	v_readlane_b32 s1, v253, 13
	s_waitcnt lgkmcnt(0)
	s_nop 3
	global_load_dword v0, v33, s[0:1] sc1
	s_waitcnt vmcnt(0)
	v_cmp_lt_u32_e32 vcc, v0, v1
	s_and_saveexec_b64 s[18:19], vcc
	s_cbranch_execz .LBB0_289
	s_mov_b32 s0, 1
	s_mov_b64 s[22:23], 0
	s_branch .LBB0_280

; __device__ __forceinline__ unsigned xb_ld(unsigned* p)              { return __hip_atomic_load(p, __ATOMIC_RELAXED, __HIP_MEMORY_SCOPE_AGENT); }
; __device__ __forceinline__ unsigned xb_add(unsigned* p, unsigned v) { return __hip_atomic_fetch_add(p, v, __ATOMIC_RELAXED, __HIP_MEMORY_SCOPE_AGENT); }
; #define XB_SPIN(cond, bar) do { unsigned _sp = 0; while (cond) { __builtin_amdgcn_s_sleep(1); \
;     if ((++_sp & 255u) == 0u) { if (xb_ld(&(bar)[XB_TMO])) break; if (_sp > XB_SPIN_CAP) { atomicAdd(&(bar)[XB_TMO], 1u); break; } } } } while (0)
; __device__ __forceinline__ void xcd_barrier(const XcdBarrier& b) {
;     ...
;             else XB_SPIN(xb_ld(&bar[XB_TOPGEN]) == tg, bar);
;             __builtin_amdgcn_fence(__ATOMIC_ACQUIRE, "agent");
;             xb_add(&bar[XB_XGEN(b.x)], 1u);
;             asm volatile("s_waitcnt vmcnt(0)" ::: "memory");
;         } else {
;             XB_SPIN(xb_ld(&bar[XB_XGEN(b.x)]) == gen, bar);
.LBB0_282:
	v_readlane_b32 s12, v253, 12
	v_readlane_b32 s13, v253, 13
	s_add_i32 s0, s0, 1
	s_mov_b64 s[40:41], -1
	s_nop 2
	global_load_dword v0, v33, s[12:13] sc1
	s_waitcnt vmcnt(0)
	v_cmp_ge_u32_e32 vcc, v0, v1
	s_orn2_b64 s[26:27], vcc, exec
	s_branch .LBB0_279

; __device__ __forceinline__ unsigned xb_ld(unsigned* p)              { return __hip_atomic_load(p, __ATOMIC_RELAXED, __HIP_MEMORY_SCOPE_AGENT); }
; __device__ __forceinline__ unsigned xb_add(unsigned* p, unsigned v) { return __hip_atomic_fetch_add(p, v, __ATOMIC_RELAXED, __HIP_MEMORY_SCOPE_AGENT); }
; #define XB_SPIN(cond, bar) do { unsigned _sp = 0; while (cond) { __builtin_amdgcn_s_sleep(1); \
;     if ((++_sp & 255u) == 0u) { if (xb_ld(&(bar)[XB_TMO])) break; if (_sp > XB_SPIN_CAP) { atomicAdd(&(bar)[XB_TMO], 1u); break; } } } } while (0)
; __device__ __forceinline__ void xcd_barrier(const XcdBarrier& b) {
;     ...
;         if (old + 1u == (gen + 1u) * nloc) {
;             __builtin_amdgcn_fence(__ATOMIC_RELEASE, "agent");
;             asm volatile("s_waitcnt vmcnt(0)" ::: "memory");
;             const unsigned og = xb_add(&bar[XB_TOP], 1u);
;             const unsigned tg = og / nx;
;             if (og + 1u == (tg + 1u) * nx) xb_add(&bar[XB_TOPGEN], 1u);
;             else XB_SPIN(xb_ld(&bar[XB_TOPGEN]) == tg, bar);
;             __builtin_amdgcn_fence(__ATOMIC_ACQUIRE, "agent");
;             xb_add(&bar[XB_XGEN(b.x)], 1u);
;             asm volatile("s_waitcnt vmcnt(0)" ::: "memory");
;         } else {
;             XB_SPIN(xb_ld(&bar[XB_XGEN(b.x)]) == gen, bar);
;             __builtin_amdgcn_fence(__ATOMIC_ACQUIRE, "agent");
;             asm volatile("s_waitcnt vmcnt(0)" ::: "memory");
;         }
;     }
;     __syncthreads();
.LBB0_290:
.LBB0_310:
	s_or_b64 exec, exec, s[16:17]
	s_mov_b32 s0, 64
	s_waitcnt lgkmcnt(0)
	s_barrier

; template <int PASS>
; __device__ __forceinline__ void rglru_phase(const Ctx& F, int l, const bf16_t* XRb, bf16_t* GRb, bool latent_only = false) {
;     ...
;                 if (lane < 16) { float h = 0.f;
; #pragma unroll 4
;                     for (int q = 0; q < NCH; ++q) { const int c = d ? (q < 4 ? 3 - q : 71 - q) : q;
;                         if (c >= c0 && c < c1) CAR[(d * 9 + (c - c0)) * 16 + lane] = h;
;                         const f32x2 ag = AB[c * 16 + lane]; h = ag[0] * h + ag[1]; } }
.LBB0_490:
	s_cmp_eq_u32 s19, 0
	s_cselect_b32 s65, 3, 0x47
	s_add_i32 s65, s65, s19
	s_add_i32 s67, s64, 1
	s_add_i32 s69, s64, 2
	s_add_i32 s77, s64, 3
	s_add_i32 s78, s65, -1
	s_add_i32 s79, s65, -2
	s_add_i32 s84, s65, -3
	s_and_b64 vcc, s[20:21], exec
	s_cselect_b32 s66, s64, s65
	s_cselect_b32 s67, s67, s78
	s_cselect_b32 s69, s69, s79
	s_cselect_b32 s77, s77, s84
	v_lshl_add_u32 v32, s66, 7, v154
	ds_read_b64 v[72:73], v32 offset:20480
	v_lshl_add_u32 v32, s67, 7, v154
	ds_read_b64 v[74:75], v32 offset:20480
	v_lshl_add_u32 v32, s69, 7, v154
	ds_read_b64 v[76:77], v32 offset:20480
	v_lshl_add_u32 v32, s77, 7, v154
	ds_read_b64 v[78:79], v32 offset:20480
	s_cmp_ge_i32 s66, s38
	s_cselect_b64 s[78:79], -1, 0
	s_cmp_lt_i32 s66, s13
	s_cselect_b64 s[84:85], -1, 0
	s_and_b64 s[78:79], s[78:79], s[84:85]
	s_andn2_b64 vcc, exec, s[78:79]
	s_cbranch_vccnz .Lcar_skip_0
	s_add_i32 s65, s18, s66
	v_lshl_add_u32 v32, s65, 6, v153
	ds_write_b32 v32, v69 offset:37120
.Lcar_skip_0:
	s_waitcnt lgkmcnt(3)
	v_fma_f32 v69, v72, v69, v73
	s_cmp_ge_i32 s67, s38
	s_cselect_b64 s[78:79], -1, 0
	s_cmp_lt_i32 s67, s13
	s_cselect_b64 s[84:85], -1, 0
	s_and_b64 s[78:79], s[78:79], s[84:85]
	s_andn2_b64 vcc, exec, s[78:79]
	s_cbranch_vccnz .Lcar_skip_1
	s_add_i32 s65, s18, s67
	v_lshl_add_u32 v32, s65, 6, v153
	ds_write_b32 v32, v69 offset:37120
.Lcar_skip_1:
	s_waitcnt lgkmcnt(2)
	v_fma_f32 v69, v74, v69, v75
	s_cmp_ge_i32 s69, s38
	s_cselect_b64 s[78:79], -1, 0
	s_cmp_lt_i32 s69, s13
	s_cselect_b64 s[84:85], -1, 0
	s_and_b64 s[78:79], s[78:79], s[84:85]
	s_andn2_b64 vcc, exec, s[78:79]
	s_cbranch_vccnz .Lcar_skip_2
	s_add_i32 s65, s18, s69
	v_lshl_add_u32 v32, s65, 6, v153
	ds_write_b32 v32, v69 offset:37120
.Lcar_skip_2:
	s_waitcnt lgkmcnt(1)
	v_fma_f32 v69, v76, v69, v77
	s_cmp_ge_i32 s77, s38
	s_cselect_b64 s[78:79], -1, 0
	s_cmp_lt_i32 s77, s13
	s_cselect_b64 s[84:85], -1, 0
	s_and_b64 s[78:79], s[78:79], s[84:85]
	s_andn2_b64 vcc, exec, s[78:79]
	s_cbranch_vccnz .Lcar_skip_3
	s_add_i32 s65, s18, s77
	v_lshl_add_u32 v32, s65, 6, v153
	ds_write_b32 v32, v69 offset:37120
.Lcar_skip_3:
	s_waitcnt lgkmcnt(0)
	v_fma_f32 v69, v78, v69, v79
	s_add_i32 s64, s64, 4
	s_add_i32 s19, s19, -4
	s_cmpk_lg_i32 s64, 0x44
	s_cbranch_scc1 .LBB0_490
	s_branch .LBB0_483

; __device__ __forceinline__ unsigned cvt_pk_bf16(float lo, float hi) { unsigned r; asm volatile("v_cvt_pk_bf16_f32 %0, %1, %2" : "=v"(r) : "v"(lo), "v"(hi)); return r; }
;     template <int LDC> __device__ __forceinline__ void store_rope(const f32x4 (&acc)[2][2][4][2], bf16_t* base, int row0, int wc, int fq) const {
;         bf16_t* rp = base + (size_t)row0 * LDC; const int axis = wc >> 1, f0 = 16 * (wc & 1) + 4 * fq;
; #pragma unroll
;         for (int ai = 0; ai < 2; ++ai)
; #pragma unroll
;             for (int m = 0; m < 4; ++m) { const int row = row0 + ai * HALF + m * 16; bf16_t* rowp = rp + (size_t)(ai * HALF + m * 16) * LDC;
;                 const int t = row & (SEQ - 1), pos = axis ? (t & 63) : (t >> 6);
;                 f32x4 cs0 = *(const f32x4*)(TAB + (pos * 32 + f0) * 2), cs1 = *(const f32x4*)(TAB + (pos * 32 + f0) * 2 + 4);
;                 if (row >= ML) { cs0 = (f32x4){1.f, 0.f, 1.f, 0.f}; cs1 = cs0; }
; #pragma unroll
;                 for (int bj = 0; bj < 2; ++bj) { const f32x4 x1 = acc[ai][bj][m][0], x2 = acc[ai][bj][m][1];
;                     u32x4 w;
;                     w.x = cvt_pk_bf16(x1[0] * cs0[0] - x2[0] * cs0[1], x1[1] * cs0[2] - x2[1] * cs0[3]);
;                     w.y = cvt_pk_bf16(x1[2] * cs1[0] - x2[2] * cs1[1], x1[3] * cs1[2] - x2[3] * cs1[3]);
;                     w.z = cvt_pk_bf16(x2[0] * cs0[0] + x1[0] * cs0[1], x2[1] * cs0[2] + x1[1] * cs0[3]);
;                     w.w = cvt_pk_bf16(x2[2] * cs1[0] + x1[2] * cs1[1], x2[3] * cs1[2] + x1[3] * cs1[3]);
;                     *(u32x4*)(rowp + bj * HALF) = w; } }
.LBB0_595:
	s_andn2_b64 vcc, exec, s[18:19]
	s_cbranch_vccnz .LBB0_597
	v_ashrrev_i32_e32 v147, 31, v146
	v_ashrrev_i32_e32 v145, 31, v144
	s_lshr_b32 s18, s45, 6
	v_lshl_add_u64 v[130:131], v[146:147], 1, s[52:53]
	v_lshlrev_b64 v[132:133], 10, v[144:145]
	v_mov_b32_e32 v147, s18
	v_lshl_add_u64 v[148:149], v[130:131], 0, v[132:133]
	v_cndmask_b32_e64 v130, v159, v147, s[40:41]
	v_lshlrev_b32_e32 v130, 5, v130
	v_lshl_add_u32 v145, v167, 2, s39
	v_and_b32_e32 v130, 0x7e0, v130
	v_add_lshl_u32 v130, v130, v145, 1
	v_ashrrev_i32_e32 v131, 31, v130
	v_lshl_add_u64 v[130:131], v[130:131], 2, s[20:21]
	global_load_dwordx4 v[176:179], v[130:131], off offset:16
	s_nop 0
	global_load_dwordx4 v[130:133], v[130:131], off
	v_or_b32_e32 v248, 16, v144
	v_cndmask_b32_e64 v248, v248, v147, s[40:41]
	v_lshlrev_b32_e32 v248, 5, v248
	v_and_b32_e32 v248, 0x7e0, v248
	v_add_lshl_u32 v248, v248, v145, 1
	v_ashrrev_i32_e32 v249, 31, v248
	v_lshl_add_u64 v[250:251], v[248:249], 2, s[20:21]
	global_load_dwordx4 v[232:235], v[250:251], off offset:16
	global_load_dwordx4 v[236:239], v[250:251], off
	s_movk_i32 s18, 0x3fff
	v_cmp_lt_i32_e32 vcc, s18, v144
	v_mov_b32_e32 v161, v108
	s_movk_i32 s18, 0x3fef
	v_mov_b32_e32 v163, v56
	s_waitcnt vmcnt(2)
	v_cndmask_b32_e64 v153, v177, 0, vcc
	v_cndmask_b32_e64 v155, v131, 0, vcc
	v_cndmask_b32_e64 v154, v130, 1.0, vcc
	v_mov_b32_e32 v130, v126
	v_mov_b32_e32 v131, v122
	v_pk_mul_f32 v[130:131], v[130:131], v[154:155]
	v_cndmask_b32_e64 v133, v133, 0, vcc
	v_cndmask_b32_e64 v132, v132, 1.0, vcc
	v_sub_f32_e32 v160, v130, v131
	v_mov_b32_e32 v130, v127
	v_mov_b32_e32 v131, v123
	v_pk_mul_f32 v[130:131], v[130:131], v[132:133]
	v_cndmask_b32_e64 v152, v176, 1.0, vcc
	v_sub_f32_e32 v130, v130, v131
	v_cvt_pk_bf16_f32 v176, v160, v130
	v_mov_b32_e32 v130, v128
	v_mov_b32_e32 v131, v124
	v_pk_mul_f32 v[130:131], v[130:131], v[152:153]
	v_cndmask_b32_e64 v151, v179, 0, vcc
	v_cndmask_b32_e64 v150, v178, 1.0, vcc
	v_sub_f32_e32 v160, v130, v131
	v_mov_b32_e32 v130, v129
	v_mov_b32_e32 v131, v125
	v_pk_mul_f32 v[130:131], v[130:131], v[150:151]
	v_cmp_lt_i32_e32 vcc, s18, v144
	v_sub_f32_e32 v130, v130, v131
	v_cvt_pk_bf16_f32 v177, v160, v130
	v_mov_b32_e32 v130, v122
	v_mov_b32_e32 v131, v126
	v_pk_mul_f32 v[130:131], v[130:131], v[154:155]
	s_movk_i32 s18, 0x4000
	v_add_f32_e32 v160, v131, v130
	v_mov_b32_e32 v130, v123
	v_mov_b32_e32 v131, v127
	v_pk_mul_f32 v[130:131], v[130:131], v[132:133]
	s_nop 0
	v_add_f32_e32 v130, v131, v130
	v_cvt_pk_bf16_f32 v178, v160, v130
	v_mov_b32_e32 v130, v124
	v_mov_b32_e32 v131, v128
	v_pk_mul_f32 v[130:131], v[130:131], v[152:153]
	s_nop 0
	v_add_f32_e32 v160, v131, v130
	v_mov_b32_e32 v130, v125
	v_mov_b32_e32 v131, v129
	v_pk_mul_f32 v[130:131], v[130:131], v[150:151]
	s_nop 0
	v_add_f32_e32 v130, v131, v130
	v_cvt_pk_bf16_f32 v179, v160, v130
	v_mov_b32_e32 v130, v114
	v_mov_b32_e32 v131, v106
	v_pk_mul_f32 v[130:131], v[130:131], v[154:155]
	global_store_dwordx4 v[148:149], v[176:179], off sc1
	v_sub_f32_e32 v160, v130, v131
	v_mov_b32_e32 v130, v115
	v_mov_b32_e32 v131, v107
	v_pk_mul_f32 v[130:131], v[130:131], v[132:133]
	s_nop 0
	v_sub_f32_e32 v130, v130, v131
	v_cvt_pk_bf16_f32 v130, v160, v130
	v_mov_b32_e32 v160, v116
	v_pk_mul_f32 v[160:161], v[160:161], v[152:153]
	s_nop 0
	v_sub_f32_e32 v131, v160, v161
	v_mov_b32_e32 v160, v117
	v_mov_b32_e32 v161, v109
	v_pk_mul_f32 v[160:161], v[160:161], v[150:151]
	s_nop 0
	v_sub_f32_e32 v160, v160, v161
	v_cvt_pk_bf16_f32 v131, v131, v160
	v_mov_b32_e32 v160, v106
	v_mov_b32_e32 v161, v114
	v_pk_mul_f32 v[154:155], v[160:161], v[154:155]
	v_mov_b32_e32 v161, v90
	v_add_f32_e32 v160, v155, v154
	v_mov_b32_e32 v154, v107
	v_mov_b32_e32 v155, v115
	v_pk_mul_f32 v[132:133], v[154:155], v[132:133]
	v_mov_b32_e32 v154, v108
	v_mov_b32_e32 v155, v116
	v_pk_mul_f32 v[152:153], v[154:155], v[152:153]
	v_add_f32_e32 v132, v133, v132
	v_add_f32_e32 v133, v153, v152
	v_mov_b32_e32 v152, v109
	v_mov_b32_e32 v153, v117
	v_pk_mul_f32 v[150:151], v[152:153], v[150:151]
	v_cvt_pk_bf16_f32 v132, v160, v132
	v_mov_b32_e32 v154, v118
	v_add_f32_e32 v150, v151, v150
	v_cvt_pk_bf16_f32 v133, v133, v150
	global_store_dwordx4 v[148:149], v[130:133], off offset:256 sc1
	v_mov_b32_e32 v155, v110
	s_nop 0
	s_waitcnt vmcnt(2)
; __device__ __forceinline__ unsigned cvt_pk_bf16(float lo, float hi) { unsigned r; asm volatile("v_cvt_pk_bf16_f32 %0, %1, %2" : "=v"(r) : "v"(lo), "v"(hi)); return r; }
;     template <int LDC> __device__ __forceinline__ void store_rope(const f32x4 (&acc)[2][2][4][2], bf16_t* base, int row0, int wc, int fq) const {
;         bf16_t* rp = base + (size_t)row0 * LDC; const int axis = wc >> 1, f0 = 16 * (wc & 1) + 4 * fq;
; #pragma unroll
;         for (int ai = 0; ai < 2; ++ai)
; #pragma unroll
;             for (int m = 0; m < 4; ++m) { const int row = row0 + ai * HALF + m * 16; bf16_t* rowp = rp + (size_t)(ai * HALF + m * 16) * LDC;
;                 const int t = row & (SEQ - 1), pos = axis ? (t & 63) : (t >> 6);
;                 f32x4 cs0 = *(const f32x4*)(TAB + (pos * 32 + f0) * 2), cs1 = *(const f32x4*)(TAB + (pos * 32 + f0) * 2 + 4);
;                 if (row >= ML) { cs0 = (f32x4){1.f, 0.f, 1.f, 0.f}; cs1 = cs0; }
; #pragma unroll
;                 for (int bj = 0; bj < 2; ++bj) { const f32x4 x1 = acc[ai][bj][m][0], x2 = acc[ai][bj][m][1];
;                     u32x4 w;
;                     w.x = cvt_pk_bf16(x1[0] * cs0[0] - x2[0] * cs0[1], x1[1] * cs0[2] - x2[1] * cs0[3]);
;                     w.y = cvt_pk_bf16(x1[2] * cs1[0] - x2[2] * cs1[1], x1[3] * cs1[2] - x2[3] * cs1[3]);
;                     w.z = cvt_pk_bf16(x2[0] * cs0[0] + x1[0] * cs0[1], x2[1] * cs0[2] + x1[1] * cs0[3]);
;                     w.w = cvt_pk_bf16(x2[2] * cs1[0] + x1[2] * cs1[1], x2[3] * cs1[2] + x1[3] * cs1[3]);
;                     *(u32x4*)(rowp + bj * HALF) = w; } }
	s_nop 1
	v_mov_b32_e32 v176, v232
	v_mov_b32_e32 v177, v233
	v_mov_b32_e32 v178, v234
	v_mov_b32_e32 v179, v235
	v_mov_b32_e32 v130, v236
	v_mov_b32_e32 v131, v237
	v_mov_b32_e32 v132, v238
	v_mov_b32_e32 v133, v239
	v_or_b32_e32 v248, 32, v144
	v_cndmask_b32_e64 v248, v248, v147, s[40:41]
	v_lshlrev_b32_e32 v248, 5, v248
	v_and_b32_e32 v248, 0x7e0, v248
	v_add_lshl_u32 v248, v248, v145, 1
	v_ashrrev_i32_e32 v249, 31, v248
	v_lshl_add_u64 v[250:251], v[248:249], 2, s[20:21]
	global_load_dwordx4 v[232:235], v[250:251], off offset:16
	global_load_dwordx4 v[236:239], v[250:251], off
	s_nop 0
	v_cndmask_b32_e64 v151, v177, 0, vcc
	v_cndmask_b32_e64 v153, v131, 0, vcc
	v_cndmask_b32_e64 v152, v130, 1.0, vcc
	v_pk_mul_f32 v[154:155], v[154:155], v[152:153]
	v_cndmask_b32_e64 v133, v133, 0, vcc
	v_cndmask_b32_e64 v132, v132, 1.0, vcc
	v_sub_f32_e32 v160, v154, v155
	v_mov_b32_e32 v154, v119
	v_mov_b32_e32 v155, v111
	v_pk_mul_f32 v[154:155], v[154:155], v[132:133]
	v_cndmask_b32_e64 v150, v176, 1.0, vcc
	v_sub_f32_e32 v154, v154, v155
	v_cvt_pk_bf16_f32 v176, v160, v154
	v_mov_b32_e32 v154, v120
	v_mov_b32_e32 v155, v112
	v_pk_mul_f32 v[154:155], v[154:155], v[150:151]
	v_cndmask_b32_e64 v131, v179, 0, vcc
	v_cndmask_b32_e64 v130, v178, 1.0, vcc
	v_sub_f32_e32 v160, v154, v155
	v_mov_b32_e32 v154, v121
	v_mov_b32_e32 v155, v113
	v_pk_mul_f32 v[154:155], v[154:155], v[130:131]
	s_nop 0
	v_sub_f32_e32 v154, v154, v155
	v_cvt_pk_bf16_f32 v177, v160, v154
	v_mov_b32_e32 v154, v110
	v_mov_b32_e32 v155, v118
	v_pk_mul_f32 v[154:155], v[154:155], v[152:153]
	s_nop 0
	v_add_f32_e32 v160, v155, v154
	v_mov_b32_e32 v154, v111
	v_mov_b32_e32 v155, v119
	v_pk_mul_f32 v[154:155], v[154:155], v[132:133]
	s_nop 0
	v_add_f32_e32 v154, v155, v154
	v_cvt_pk_bf16_f32 v178, v160, v154
	v_mov_b32_e32 v154, v112
	v_mov_b32_e32 v155, v120
	v_pk_mul_f32 v[154:155], v[154:155], v[150:151]
	s_nop 0
	v_add_f32_e32 v160, v155, v154
	v_mov_b32_e32 v154, v113
	v_mov_b32_e32 v155, v121
	v_pk_mul_f32 v[154:155], v[154:155], v[130:131]
	s_nop 0
	v_add_f32_e32 v154, v155, v154
	v_cvt_pk_bf16_f32 v179, v160, v154
	v_mov_b32_e32 v160, v98
	v_pk_mul_f32 v[160:161], v[160:161], v[152:153]
	v_add_co_u32_e32 v154, vcc, s18, v148
	v_sub_f32_e32 v162, v160, v161
	v_mov_b32_e32 v160, v99
	v_mov_b32_e32 v161, v91
	v_pk_mul_f32 v[160:161], v[160:161], v[132:133]
	v_addc_co_u32_e32 v155, vcc, 0, v149, vcc
	v_sub_f32_e32 v160, v160, v161
	global_store_dwordx4 v[154:155], v[176:179], off sc1
	v_mov_b32_e32 v161, v92
	s_movk_i32 s18, 0x3fdf
	v_cvt_pk_bf16_f32 v176, v162, v160
	v_mov_b32_e32 v160, v100
	v_pk_mul_f32 v[160:161], v[160:161], v[150:151]
	v_cmp_lt_i32_e32 vcc, s18, v144
	v_sub_f32_e32 v162, v160, v161
	v_mov_b32_e32 v160, v101
	v_mov_b32_e32 v161, v93
	v_pk_mul_f32 v[160:161], v[160:161], v[130:131]
	s_mov_b32 s18, 0x8000
	v_sub_f32_e32 v160, v160, v161
	v_cvt_pk_bf16_f32 v177, v162, v160
	v_mov_b32_e32 v160, v90
	v_mov_b32_e32 v161, v98
	v_pk_mul_f32 v[152:153], v[160:161], v[152:153]
	v_mov_b32_e32 v161, v74
	v_add_f32_e32 v160, v153, v152
	v_mov_b32_e32 v152, v91
	v_mov_b32_e32 v153, v99
	v_pk_mul_f32 v[132:133], v[152:153], v[132:133]
	s_nop 0
	v_add_f32_e32 v132, v133, v132
	v_cvt_pk_bf16_f32 v178, v160, v132
	v_mov_b32_e32 v132, v92
	v_mov_b32_e32 v133, v100
	v_pk_mul_f32 v[132:133], v[132:133], v[150:151]
	s_nop 0
	v_add_f32_e32 v150, v133, v132
	v_mov_b32_e32 v132, v93
	v_mov_b32_e32 v133, v101
	v_pk_mul_f32 v[130:131], v[132:133], v[130:131]
	s_nop 0
	v_add_f32_e32 v130, v131, v130
	v_cvt_pk_bf16_f32 v179, v150, v130
	global_store_dwordx4 v[154:155], v[176:179], off offset:256 sc1
	s_waitcnt vmcnt(2)
	s_nop 1
	v_mov_b32_e32 v176, v232
	v_mov_b32_e32 v177, v233
	v_mov_b32_e32 v178, v234
	v_mov_b32_e32 v179, v235
	v_mov_b32_e32 v130, v236
	v_mov_b32_e32 v131, v237
	v_mov_b32_e32 v132, v238
	v_mov_b32_e32 v133, v239
	v_or_b32_e32 v248, 48, v144
	v_cndmask_b32_e64 v248, v248, v147, s[40:41]
	v_lshlrev_b32_e32 v248, 5, v248
	v_and_b32_e32 v248, 0x7e0, v248
	v_add_lshl_u32 v248, v248, v145, 1
	v_ashrrev_i32_e32 v249, 31, v248
	v_lshl_add_u64 v[250:251], v[248:249], 2, s[20:21]
	global_load_dwordx4 v[232:235], v[250:251], off offset:16
	global_load_dwordx4 v[236:239], v[250:251], off
	s_nop 0
	v_mov_b32_e32 v154, v102
	v_mov_b32_e32 v155, v94
	v_cndmask_b32_e64 v151, v177, 0, vcc
	v_cndmask_b32_e64 v153, v131, 0, vcc
	v_cndmask_b32_e64 v152, v130, 1.0, vcc
	v_pk_mul_f32 v[154:155], v[154:155], v[152:153]
	v_cndmask_b32_e64 v133, v133, 0, vcc
	v_cndmask_b32_e64 v132, v132, 1.0, vcc
	v_sub_f32_e32 v160, v154, v155
	v_mov_b32_e32 v154, v103
	v_mov_b32_e32 v155, v95
	v_pk_mul_f32 v[154:155], v[154:155], v[132:133]
	v_cndmask_b32_e64 v150, v176, 1.0, vcc
	v_sub_f32_e32 v154, v154, v155
	v_cvt_pk_bf16_f32 v176, v160, v154
	v_mov_b32_e32 v154, v104
	v_mov_b32_e32 v155, v96
	v_pk_mul_f32 v[154:155], v[154:155], v[150:151]
	v_cndmask_b32_e64 v131, v179, 0, vcc
	v_cndmask_b32_e64 v130, v178, 1.0, vcc
	v_sub_f32_e32 v160, v154, v155
	v_mov_b32_e32 v154, v105
	v_mov_b32_e32 v155, v97
	v_pk_mul_f32 v[154:155], v[154:155], v[130:131]
	s_nop 0
	v_sub_f32_e32 v154, v154, v155
	v_cvt_pk_bf16_f32 v177, v160, v154
	v_mov_b32_e32 v154, v94
	v_mov_b32_e32 v155, v102
	v_pk_mul_f32 v[154:155], v[154:155], v[152:153]
	s_nop 0
	v_add_f32_e32 v160, v155, v154
	v_mov_b32_e32 v154, v95
	v_mov_b32_e32 v155, v103
	v_pk_mul_f32 v[154:155], v[154:155], v[132:133]
	s_nop 0
	v_add_f32_e32 v154, v155, v154
	v_cvt_pk_bf16_f32 v178, v160, v154
	v_mov_b32_e32 v154, v96
	v_mov_b32_e32 v155, v104
	v_pk_mul_f32 v[154:155], v[154:155], v[150:151]
	s_nop 0
	v_add_f32_e32 v160, v155, v154
	v_mov_b32_e32 v154, v97
; __device__ __forceinline__ unsigned cvt_pk_bf16(float lo, float hi) { unsigned r; asm volatile("v_cvt_pk_bf16_f32 %0, %1, %2" : "=v"(r) : "v"(lo), "v"(hi)); return r; }
;     template <int LDC> __device__ __forceinline__ void store_rope(const f32x4 (&acc)[2][2][4][2], bf16_t* base, int row0, int wc, int fq) const {
;         bf16_t* rp = base + (size_t)row0 * LDC; const int axis = wc >> 1, f0 = 16 * (wc & 1) + 4 * fq;
; #pragma unroll
;         for (int ai = 0; ai < 2; ++ai)
; #pragma unroll
;             for (int m = 0; m < 4; ++m) { const int row = row0 + ai * HALF + m * 16; bf16_t* rowp = rp + (size_t)(ai * HALF + m * 16) * LDC;
;                 const int t = row & (SEQ - 1), pos = axis ? (t & 63) : (t >> 6);
;                 f32x4 cs0 = *(const f32x4*)(TAB + (pos * 32 + f0) * 2), cs1 = *(const f32x4*)(TAB + (pos * 32 + f0) * 2 + 4);
;                 if (row >= ML) { cs0 = (f32x4){1.f, 0.f, 1.f, 0.f}; cs1 = cs0; }
; #pragma unroll
;                 for (int bj = 0; bj < 2; ++bj) { const f32x4 x1 = acc[ai][bj][m][0], x2 = acc[ai][bj][m][1];
;                     u32x4 w;
;                     w.x = cvt_pk_bf16(x1[0] * cs0[0] - x2[0] * cs0[1], x1[1] * cs0[2] - x2[1] * cs0[3]);
;                     w.y = cvt_pk_bf16(x1[2] * cs1[0] - x2[2] * cs1[1], x1[3] * cs1[2] - x2[3] * cs1[3]);
;                     w.z = cvt_pk_bf16(x2[0] * cs0[0] + x1[0] * cs0[1], x2[1] * cs0[2] + x1[1] * cs0[3]);
;                     w.w = cvt_pk_bf16(x2[2] * cs1[0] + x1[2] * cs1[1], x2[3] * cs1[2] + x1[3] * cs1[3]);
;                     *(u32x4*)(rowp + bj * HALF) = w; } }
	v_mov_b32_e32 v155, v105
	v_pk_mul_f32 v[154:155], v[154:155], v[130:131]
	s_nop 0
	v_add_f32_e32 v154, v155, v154
	v_cvt_pk_bf16_f32 v179, v160, v154
	v_mov_b32_e32 v160, v82
	v_pk_mul_f32 v[160:161], v[160:161], v[152:153]
	v_add_co_u32_e32 v154, vcc, s18, v148
	v_sub_f32_e32 v162, v160, v161
	v_mov_b32_e32 v160, v83
	v_mov_b32_e32 v161, v75
	v_pk_mul_f32 v[160:161], v[160:161], v[132:133]
	v_addc_co_u32_e32 v155, vcc, 0, v149, vcc
	v_sub_f32_e32 v160, v160, v161
	global_store_dwordx4 v[154:155], v[176:179], off sc1
	v_mov_b32_e32 v161, v76
	s_movk_i32 s18, 0x3fcf
	v_cvt_pk_bf16_f32 v176, v162, v160
	v_mov_b32_e32 v160, v84
	v_pk_mul_f32 v[160:161], v[160:161], v[150:151]
	v_cmp_lt_i32_e32 vcc, s18, v144
	v_sub_f32_e32 v162, v160, v161
	v_mov_b32_e32 v160, v85
	v_mov_b32_e32 v161, v77
	v_pk_mul_f32 v[160:161], v[160:161], v[130:131]
	s_add_i32 s18, s45, 0x80
	v_sub_f32_e32 v160, v160, v161
	v_cvt_pk_bf16_f32 v177, v162, v160
	v_mov_b32_e32 v160, v74
	v_mov_b32_e32 v161, v82
	v_pk_mul_f32 v[152:153], v[160:161], v[152:153]
	v_mov_b32_e32 v161, v66
	v_add_f32_e32 v160, v153, v152
	v_mov_b32_e32 v152, v75
	v_mov_b32_e32 v153, v83
	v_pk_mul_f32 v[132:133], v[152:153], v[132:133]
	s_lshr_b32 s18, s18, 6
	v_add_f32_e32 v132, v133, v132
	v_cvt_pk_bf16_f32 v178, v160, v132
	v_mov_b32_e32 v132, v76
	v_mov_b32_e32 v133, v84
	v_pk_mul_f32 v[132:133], v[132:133], v[150:151]
	v_mov_b32_e32 v160, v70
	v_add_f32_e32 v150, v133, v132
	v_mov_b32_e32 v132, v77
	v_mov_b32_e32 v133, v85
	v_pk_mul_f32 v[130:131], v[132:133], v[130:131]
	v_mov_b32_e32 v162, v48
	v_add_f32_e32 v130, v131, v130
	v_cvt_pk_bf16_f32 v179, v150, v130
	global_store_dwordx4 v[154:155], v[176:179], off offset:256 sc1
	s_waitcnt vmcnt(2)
	s_nop 1
	v_mov_b32_e32 v176, v232
	v_mov_b32_e32 v177, v233
	v_mov_b32_e32 v178, v234
	v_mov_b32_e32 v179, v235
	v_mov_b32_e32 v130, v236
	v_mov_b32_e32 v131, v237
	v_mov_b32_e32 v132, v238
	v_mov_b32_e32 v133, v239
	v_mov_b32_e32 v248, s18
	v_cndmask_b32_e64 v248, v159, v248, s[40:41]
	v_lshlrev_b32_e32 v248, 5, v248
	v_and_b32_e32 v248, 0x7e0, v248
	v_add_lshl_u32 v248, v248, v145, 1
	v_ashrrev_i32_e32 v249, 31, v248
	v_lshl_add_u64 v[250:251], v[248:249], 2, s[20:21]
	global_load_dwordx4 v[232:235], v[250:251], off offset:16
	global_load_dwordx4 v[236:239], v[250:251], off
	s_nop 0
	v_mov_b32_e32 v154, v86
	v_mov_b32_e32 v155, v78
	v_cndmask_b32_e64 v151, v177, 0, vcc
	v_cndmask_b32_e64 v153, v131, 0, vcc
	v_cndmask_b32_e64 v152, v130, 1.0, vcc
	v_pk_mul_f32 v[154:155], v[154:155], v[152:153]
	v_cndmask_b32_e64 v133, v133, 0, vcc
	v_cndmask_b32_e64 v132, v132, 1.0, vcc
	v_sub_f32_e32 v147, v154, v155
	v_mov_b32_e32 v154, v87
	v_mov_b32_e32 v155, v79
	v_pk_mul_f32 v[154:155], v[154:155], v[132:133]
	v_cndmask_b32_e64 v150, v176, 1.0, vcc
	v_sub_f32_e32 v154, v154, v155
	v_cvt_pk_bf16_f32 v176, v147, v154
	v_mov_b32_e32 v154, v88
	v_mov_b32_e32 v155, v80
	v_pk_mul_f32 v[154:155], v[154:155], v[150:151]
	v_cndmask_b32_e64 v131, v179, 0, vcc
	v_cndmask_b32_e64 v130, v178, 1.0, vcc
	v_sub_f32_e32 v147, v154, v155
	v_mov_b32_e32 v154, v89
	v_mov_b32_e32 v155, v81
	v_pk_mul_f32 v[154:155], v[154:155], v[130:131]
	v_pk_mul_f32 v[160:161], v[160:161], v[152:153]
	v_sub_f32_e32 v154, v154, v155
	v_cvt_pk_bf16_f32 v177, v147, v154
	v_mov_b32_e32 v154, v78
	v_mov_b32_e32 v155, v86
	v_pk_mul_f32 v[154:155], v[154:155], v[152:153]
	s_nop 0
	v_add_f32_e32 v147, v155, v154
	v_mov_b32_e32 v154, v79
	v_mov_b32_e32 v155, v87
	v_pk_mul_f32 v[154:155], v[154:155], v[132:133]
	s_nop 0
	v_add_f32_e32 v154, v155, v154
	v_cvt_pk_bf16_f32 v178, v147, v154
	v_mov_b32_e32 v154, v80
	v_mov_b32_e32 v155, v88
	v_pk_mul_f32 v[154:155], v[154:155], v[150:151]
	s_nop 0
	v_add_f32_e32 v147, v155, v154
	v_mov_b32_e32 v154, v81
	v_mov_b32_e32 v155, v89
	v_pk_mul_f32 v[154:155], v[154:155], v[130:131]
	s_nop 0
	v_add_f32_e32 v154, v155, v154
	v_cvt_pk_bf16_f32 v179, v147, v154
	v_sub_f32_e32 v147, v160, v161
	v_mov_b32_e32 v160, v71
	v_mov_b32_e32 v161, v67
	v_add_co_u32_e32 v154, vcc, s95, v148
	v_pk_mul_f32 v[160:161], v[160:161], v[132:133]
	s_nop 0
	v_addc_co_u32_e32 v155, vcc, 0, v149, vcc
	v_sub_f32_e32 v160, v160, v161
	global_store_dwordx4 v[154:155], v[176:179], off sc1
	v_mov_b32_e32 v161, v68
	s_nop 0
	v_cvt_pk_bf16_f32 v176, v147, v160
	v_mov_b32_e32 v160, v72
	v_pk_mul_f32 v[160:161], v[160:161], v[150:151]
	s_nop 0
	v_sub_f32_e32 v147, v160, v161
	v_mov_b32_e32 v160, v73
	v_mov_b32_e32 v161, v69
	v_pk_mul_f32 v[160:161], v[160:161], v[130:131]
	s_nop 0
	v_sub_f32_e32 v160, v160, v161
	v_cvt_pk_bf16_f32 v177, v147, v160
	v_mov_b32_e32 v160, v66
	v_mov_b32_e32 v161, v70
	v_pk_mul_f32 v[152:153], v[160:161], v[152:153]
	v_mov_b32_e32 v160, v50
	v_add_f32_e32 v147, v153, v152
	v_mov_b32_e32 v152, v67
	v_mov_b32_e32 v153, v71
	v_pk_mul_f32 v[132:133], v[152:153], v[132:133]
	v_mov_b32_e32 v161, v42
	v_add_f32_e32 v132, v133, v132
	v_cvt_pk_bf16_f32 v178, v147, v132
	v_mov_b32_e32 v132, v68
	v_mov_b32_e32 v133, v72
	v_pk_mul_f32 v[132:133], v[132:133], v[150:151]
	s_nop 0
	v_add_f32_e32 v147, v133, v132
	v_mov_b32_e32 v132, v69
	v_mov_b32_e32 v133, v73
	v_pk_mul_f32 v[130:131], v[132:133], v[130:131]
	s_nop 0
	v_add_f32_e32 v130, v131, v130
	v_cvt_pk_bf16_f32 v179, v147, v130
	global_store_dwordx4 v[154:155], v[176:179], off offset:256 sc1
	s_waitcnt vmcnt(2)
; __device__ __forceinline__ unsigned cvt_pk_bf16(float lo, float hi) { unsigned r; asm volatile("v_cvt_pk_bf16_f32 %0, %1, %2" : "=v"(r) : "v"(lo), "v"(hi)); return r; }
;     template <int LDC> __device__ __forceinline__ void store_rope(const f32x4 (&acc)[2][2][4][2], bf16_t* base, int row0, int wc, int fq) const {
;         bf16_t* rp = base + (size_t)row0 * LDC; const int axis = wc >> 1, f0 = 16 * (wc & 1) + 4 * fq;
; #pragma unroll
;         for (int ai = 0; ai < 2; ++ai)
; #pragma unroll
;             for (int m = 0; m < 4; ++m) { const int row = row0 + ai * HALF + m * 16; bf16_t* rowp = rp + (size_t)(ai * HALF + m * 16) * LDC;
;                 const int t = row & (SEQ - 1), pos = axis ? (t & 63) : (t >> 6);
;                 f32x4 cs0 = *(const f32x4*)(TAB + (pos * 32 + f0) * 2), cs1 = *(const f32x4*)(TAB + (pos * 32 + f0) * 2 + 4);
;                 if (row >= ML) { cs0 = (f32x4){1.f, 0.f, 1.f, 0.f}; cs1 = cs0; }
; #pragma unroll
;                 for (int bj = 0; bj < 2; ++bj) { const f32x4 x1 = acc[ai][bj][m][0], x2 = acc[ai][bj][m][1];
;                     u32x4 w;
;                     w.x = cvt_pk_bf16(x1[0] * cs0[0] - x2[0] * cs0[1], x1[1] * cs0[2] - x2[1] * cs0[3]);
;                     w.y = cvt_pk_bf16(x1[2] * cs1[0] - x2[2] * cs1[1], x1[3] * cs1[2] - x2[3] * cs1[3]);
;                     w.z = cvt_pk_bf16(x2[0] * cs0[0] + x1[0] * cs0[1], x2[1] * cs0[2] + x1[1] * cs0[3]);
;                     w.w = cvt_pk_bf16(x2[2] * cs1[0] + x1[2] * cs1[1], x2[3] * cs1[2] + x1[3] * cs1[3]);
;                     *(u32x4*)(rowp + bj * HALF) = w; } }
	s_nop 1
	v_mov_b32_e32 v176, v232
	v_mov_b32_e32 v177, v233
	v_mov_b32_e32 v178, v234
	v_mov_b32_e32 v179, v235
	v_mov_b32_e32 v130, v236
	v_mov_b32_e32 v131, v237
	v_mov_b32_e32 v132, v238
	v_mov_b32_e32 v133, v239
	v_add_u32_e32 v248, 0x90, v144
	v_lshrrev_b32_e32 v249, 6, v248
	v_cndmask_b32_e64 v248, v248, v249, s[40:41]
	v_lshlrev_b32_e32 v248, 5, v248
	v_and_b32_e32 v248, 0x7e0, v248
	v_add_lshl_u32 v248, v248, v145, 1
	v_ashrrev_i32_e32 v249, 31, v248
	v_lshl_add_u64 v[250:251], v[248:249], 2, s[20:21]
	global_load_dwordx4 v[232:235], v[250:251], off offset:16
	global_load_dwordx4 v[236:239], v[250:251], off
	s_nop 0
	s_movk_i32 s18, 0x3f7f
	v_cmp_lt_i32_e32 vcc, s18, v144
	v_mov_b32_e32 v154, v62
	v_mov_b32_e32 v155, v58
	s_mov_b32 s18, 0x20000
	v_cndmask_b32_e64 v151, v177, 0, vcc
	v_cndmask_b32_e64 v153, v131, 0, vcc
	v_cndmask_b32_e64 v152, v130, 1.0, vcc
	v_pk_mul_f32 v[154:155], v[154:155], v[152:153]
	v_cndmask_b32_e64 v133, v133, 0, vcc
	v_cndmask_b32_e64 v132, v132, 1.0, vcc
	v_sub_f32_e32 v147, v154, v155
	v_mov_b32_e32 v154, v63
	v_mov_b32_e32 v155, v59
	v_pk_mul_f32 v[154:155], v[154:155], v[132:133]
	v_cndmask_b32_e64 v150, v176, 1.0, vcc
	v_sub_f32_e32 v154, v154, v155
	v_cvt_pk_bf16_f32 v176, v147, v154
	v_mov_b32_e32 v154, v64
	v_mov_b32_e32 v155, v60
	v_pk_mul_f32 v[154:155], v[154:155], v[150:151]
	v_cndmask_b32_e64 v131, v179, 0, vcc
	v_cndmask_b32_e64 v130, v178, 1.0, vcc
	v_sub_f32_e32 v147, v154, v155
	v_mov_b32_e32 v154, v65
	v_mov_b32_e32 v155, v61
	v_pk_mul_f32 v[154:155], v[154:155], v[130:131]
	v_pk_mul_f32 v[160:161], v[160:161], v[152:153]
	v_sub_f32_e32 v154, v154, v155
	v_cvt_pk_bf16_f32 v177, v147, v154
	v_mov_b32_e32 v154, v58
	v_mov_b32_e32 v155, v62
	v_pk_mul_f32 v[154:155], v[154:155], v[152:153]
	s_nop 0
	v_add_f32_e32 v147, v155, v154
	v_mov_b32_e32 v154, v59
	v_mov_b32_e32 v155, v63
	v_pk_mul_f32 v[154:155], v[154:155], v[132:133]
	s_nop 0
	v_add_f32_e32 v154, v155, v154
	v_cvt_pk_bf16_f32 v178, v147, v154
	v_mov_b32_e32 v154, v60
	v_mov_b32_e32 v155, v64
	v_pk_mul_f32 v[154:155], v[154:155], v[150:151]
	s_nop 0
	v_add_f32_e32 v147, v155, v154
	v_mov_b32_e32 v154, v61
	v_mov_b32_e32 v155, v65
	v_pk_mul_f32 v[154:155], v[154:155], v[130:131]
	s_nop 0
	v_add_f32_e32 v154, v155, v154
	v_cvt_pk_bf16_f32 v179, v147, v154
	v_sub_f32_e32 v147, v160, v161
	v_mov_b32_e32 v160, v51
	v_mov_b32_e32 v161, v43
	v_add_co_u32_e32 v154, vcc, s18, v148
	v_pk_mul_f32 v[160:161], v[160:161], v[132:133]
	s_nop 0
	v_addc_co_u32_e32 v155, vcc, 0, v149, vcc
	v_sub_f32_e32 v160, v160, v161
	global_store_dwordx4 v[154:155], v[176:179], off sc1
	v_mov_b32_e32 v161, v44
	s_movk_i32 s18, 0x3f6f
	v_cvt_pk_bf16_f32 v176, v147, v160
	v_mov_b32_e32 v160, v52
	v_pk_mul_f32 v[160:161], v[160:161], v[150:151]
	v_cmp_lt_i32_e32 vcc, s18, v144
	v_sub_f32_e32 v147, v160, v161
	v_mov_b32_e32 v160, v53
	v_mov_b32_e32 v161, v45
	v_pk_mul_f32 v[160:161], v[160:161], v[130:131]
	s_movk_i32 s18, 0x3f5f
	v_sub_f32_e32 v160, v160, v161
	v_cvt_pk_bf16_f32 v177, v147, v160
	v_mov_b32_e32 v160, v42
	v_mov_b32_e32 v161, v50
	v_pk_mul_f32 v[152:153], v[160:161], v[152:153]
	s_nop 0
	v_add_f32_e32 v147, v153, v152
	v_mov_b32_e32 v152, v43
	v_mov_b32_e32 v153, v51
	v_pk_mul_f32 v[132:133], v[152:153], v[132:133]
	s_nop 0
	v_add_f32_e32 v132, v133, v132
	v_cvt_pk_bf16_f32 v178, v147, v132
	v_mov_b32_e32 v132, v44
	v_mov_b32_e32 v133, v52
	v_pk_mul_f32 v[132:133], v[132:133], v[150:151]
	s_nop 0
	v_add_f32_e32 v147, v133, v132
	v_mov_b32_e32 v132, v45
	v_mov_b32_e32 v133, v53
	v_pk_mul_f32 v[130:131], v[132:133], v[130:131]
	s_nop 0
	v_add_f32_e32 v130, v131, v130
	v_cvt_pk_bf16_f32 v179, v147, v130
	global_store_dwordx4 v[154:155], v[176:179], off offset:256 sc1
	s_waitcnt vmcnt(2)
	s_nop 1
	v_mov_b32_e32 v130, v232
	v_mov_b32_e32 v131, v233
	v_mov_b32_e32 v132, v234
	v_mov_b32_e32 v133, v235
	v_mov_b32_e32 v150, v236
	v_mov_b32_e32 v151, v237
	v_mov_b32_e32 v152, v238
	v_mov_b32_e32 v153, v239
	v_add_u32_e32 v248, 0xa0, v144
	v_lshrrev_b32_e32 v249, 6, v248
	v_cndmask_b32_e64 v248, v248, v249, s[40:41]
	v_lshlrev_b32_e32 v248, 5, v248
	v_and_b32_e32 v248, 0x7e0, v248
	v_add_lshl_u32 v248, v248, v145, 1
	v_ashrrev_i32_e32 v249, 31, v248
	v_lshl_add_u64 v[250:251], v[248:249], 2, s[20:21]
	global_load_dwordx4 v[232:235], v[250:251], off offset:16
	global_load_dwordx4 v[236:239], v[250:251], off
	s_nop 0
	v_cndmask_b32_e64 v161, v131, 0, vcc
	v_cndmask_b32_e64 v151, v151, 0, vcc
	v_cndmask_b32_e64 v150, v150, 1.0, vcc
	v_cndmask_b32_e64 v160, v130, 1.0, vcc
	v_mov_b32_e32 v130, v54
	v_mov_b32_e32 v131, v46
	v_pk_mul_f32 v[130:131], v[130:131], v[150:151]
	v_cndmask_b32_e64 v153, v153, 0, vcc
	v_cndmask_b32_e64 v152, v152, 1.0, vcc
	v_cndmask_b32_e64 v154, v132, 1.0, vcc
	v_sub_f32_e32 v132, v130, v131
	v_mov_b32_e32 v130, v55
	v_mov_b32_e32 v131, v47
	v_pk_mul_f32 v[130:131], v[130:131], v[152:153]
	v_cndmask_b32_e64 v155, v133, 0, vcc
	v_sub_f32_e32 v130, v130, v131
	v_cvt_pk_bf16_f32 v130, v132, v130
	v_mov_b32_e32 v132, v56
	v_mov_b32_e32 v133, v48
	v_pk_mul_f32 v[132:133], v[132:133], v[160:161]
	v_pk_mul_f32 v[162:163], v[162:163], v[160:161]
	v_sub_f32_e32 v131, v132, v133
	v_mov_b32_e32 v132, v57
	v_mov_b32_e32 v133, v49
	v_pk_mul_f32 v[132:133], v[132:133], v[154:155]
	s_nop 0
	v_sub_f32_e32 v132, v132, v133
	v_cvt_pk_bf16_f32 v131, v131, v132
	v_mov_b32_e32 v132, v46
	v_mov_b32_e32 v133, v54
	v_pk_mul_f32 v[132:133], v[132:133], v[150:151]
	s_nop 0
	v_add_f32_e32 v147, v133, v132
	v_mov_b32_e32 v132, v47
	v_mov_b32_e32 v133, v55
	v_pk_mul_f32 v[132:133], v[132:133], v[152:153]
	s_nop 0
	v_add_f32_e32 v132, v133, v132
	v_add_f32_e32 v133, v163, v162
; __device__ __forceinline__ unsigned cvt_pk_bf16(float lo, float hi) { unsigned r; asm volatile("v_cvt_pk_bf16_f32 %0, %1, %2" : "=v"(r) : "v"(lo), "v"(hi)); return r; }
;     template <int LDC> __device__ __forceinline__ void store_rope(const f32x4 (&acc)[2][2][4][2], bf16_t* base, int row0, int wc, int fq) const {
;         bf16_t* rp = base + (size_t)row0 * LDC; const int axis = wc >> 1, f0 = 16 * (wc & 1) + 4 * fq;
; #pragma unroll
;         for (int ai = 0; ai < 2; ++ai)
; #pragma unroll
;             for (int m = 0; m < 4; ++m) { const int row = row0 + ai * HALF + m * 16; bf16_t* rowp = rp + (size_t)(ai * HALF + m * 16) * LDC;
;                 const int t = row & (SEQ - 1), pos = axis ? (t & 63) : (t >> 6);
;                 f32x4 cs0 = *(const f32x4*)(TAB + (pos * 32 + f0) * 2), cs1 = *(const f32x4*)(TAB + (pos * 32 + f0) * 2 + 4);
;                 if (row >= ML) { cs0 = (f32x4){1.f, 0.f, 1.f, 0.f}; cs1 = cs0; }
; #pragma unroll
;                 for (int bj = 0; bj < 2; ++bj) { const f32x4 x1 = acc[ai][bj][m][0], x2 = acc[ai][bj][m][1];
;                     u32x4 w;
;                     w.x = cvt_pk_bf16(x1[0] * cs0[0] - x2[0] * cs0[1], x1[1] * cs0[2] - x2[1] * cs0[3]);
;                     w.y = cvt_pk_bf16(x1[2] * cs1[0] - x2[2] * cs1[1], x1[3] * cs1[2] - x2[3] * cs1[3]);
;                     w.z = cvt_pk_bf16(x2[0] * cs0[0] + x1[0] * cs0[1], x2[1] * cs0[2] + x1[1] * cs0[3]);
;                     w.w = cvt_pk_bf16(x2[2] * cs1[0] + x1[2] * cs1[1], x2[3] * cs1[2] + x1[3] * cs1[3]);
;                     *(u32x4*)(rowp + bj * HALF) = w; } }
	v_mov_b32_e32 v162, v49
	v_mov_b32_e32 v163, v57
	v_pk_mul_f32 v[162:163], v[162:163], v[154:155]
	v_cvt_pk_bf16_f32 v132, v147, v132
	s_nop 0
	v_add_f32_e32 v147, v163, v162
	v_add_co_u32_e32 v162, vcc, s83, v148
	v_cvt_pk_bf16_f32 v133, v133, v147
	s_nop 1
	v_addc_co_u32_e32 v163, vcc, 0, v149, vcc
	global_store_dwordx4 v[162:163], v[130:133], off sc1
	v_cmp_lt_i32_e32 vcc, s18, v144
	s_mov_b32 s18, 0x28000
	v_mov_b32_e32 v130, v34
	v_mov_b32_e32 v131, v24
	v_pk_mul_f32 v[130:131], v[130:131], v[150:151]
	v_mov_b32_e32 v133, v26
	v_sub_f32_e32 v132, v130, v131
	v_mov_b32_e32 v130, v35
	v_mov_b32_e32 v131, v25
	v_pk_mul_f32 v[130:131], v[130:131], v[152:153]
	s_nop 0
	v_sub_f32_e32 v130, v130, v131
	v_cvt_pk_bf16_f32 v130, v132, v130
	v_mov_b32_e32 v132, v36
	v_pk_mul_f32 v[132:133], v[132:133], v[160:161]
	s_nop 0
	v_sub_f32_e32 v131, v132, v133
	v_mov_b32_e32 v132, v37
	v_mov_b32_e32 v133, v27
	v_pk_mul_f32 v[132:133], v[132:133], v[154:155]
	s_nop 0
	v_sub_f32_e32 v132, v132, v133
	v_cvt_pk_bf16_f32 v131, v131, v132
	v_mov_b32_e32 v132, v24
	v_mov_b32_e32 v133, v34
	v_pk_mul_f32 v[132:133], v[132:133], v[150:151]
	v_mov_b32_e32 v150, v26
	v_add_f32_e32 v147, v133, v132
	v_mov_b32_e32 v132, v25
	v_mov_b32_e32 v133, v35
	v_mov_b32_e32 v151, v36
	v_pk_mul_f32 v[132:133], v[132:133], v[152:153]
	v_pk_mul_f32 v[150:151], v[150:151], v[160:161]
	v_add_f32_e32 v132, v133, v132
	v_add_f32_e32 v133, v151, v150
	v_mov_b32_e32 v150, v27
	v_mov_b32_e32 v151, v37
	v_pk_mul_f32 v[150:151], v[150:151], v[154:155]
	v_cvt_pk_bf16_f32 v132, v147, v132
	s_nop 0
	v_add_f32_e32 v147, v151, v150
	v_cvt_pk_bf16_f32 v133, v133, v147
	global_store_dwordx4 v[162:163], v[130:133], off offset:256 sc1
	v_mov_b32_e32 v162, v30
	v_mov_b32_e32 v163, v40
	s_waitcnt vmcnt(2)
	s_nop 1
	v_mov_b32_e32 v130, v232
	v_mov_b32_e32 v131, v233
	v_mov_b32_e32 v132, v234
	v_mov_b32_e32 v133, v235
	v_mov_b32_e32 v150, v236
	v_mov_b32_e32 v151, v237
	v_mov_b32_e32 v152, v238
	v_mov_b32_e32 v153, v239
	v_add_u32_e32 v248, 0xb0, v144
	v_lshrrev_b32_e32 v249, 6, v248
	v_cndmask_b32_e64 v248, v248, v249, s[40:41]
	v_lshlrev_b32_e32 v248, 5, v248
	v_and_b32_e32 v248, 0x7e0, v248
	v_add_lshl_u32 v248, v248, v145, 1
	v_ashrrev_i32_e32 v249, 31, v248
	v_lshl_add_u64 v[250:251], v[248:249], 2, s[20:21]
	global_load_dwordx4 v[232:235], v[250:251], off offset:16
	global_load_dwordx4 v[236:239], v[250:251], off
	s_nop 0
	v_cndmask_b32_e64 v161, v131, 0, vcc
	v_cndmask_b32_e64 v151, v151, 0, vcc
	v_cndmask_b32_e64 v150, v150, 1.0, vcc
	v_cndmask_b32_e64 v160, v130, 1.0, vcc
	v_mov_b32_e32 v130, v38
	v_mov_b32_e32 v131, v28
	v_pk_mul_f32 v[130:131], v[130:131], v[150:151]
	v_cndmask_b32_e64 v153, v153, 0, vcc
	v_cndmask_b32_e64 v152, v152, 1.0, vcc
	v_cndmask_b32_e64 v154, v132, 1.0, vcc
	v_sub_f32_e32 v132, v130, v131
	v_mov_b32_e32 v130, v39
	v_mov_b32_e32 v131, v29
	v_pk_mul_f32 v[130:131], v[130:131], v[152:153]
	v_cndmask_b32_e64 v155, v133, 0, vcc
	v_sub_f32_e32 v130, v130, v131
	v_cvt_pk_bf16_f32 v130, v132, v130
	v_mov_b32_e32 v132, v40
	v_mov_b32_e32 v133, v30
	v_pk_mul_f32 v[132:133], v[132:133], v[160:161]
	v_pk_mul_f32 v[162:163], v[162:163], v[160:161]
	v_sub_f32_e32 v131, v132, v133
	v_mov_b32_e32 v132, v41
	v_mov_b32_e32 v133, v31
	v_pk_mul_f32 v[132:133], v[132:133], v[154:155]
	s_nop 0
	v_sub_f32_e32 v132, v132, v133
	v_cvt_pk_bf16_f32 v131, v131, v132
	v_mov_b32_e32 v132, v28
	v_mov_b32_e32 v133, v38
	v_pk_mul_f32 v[132:133], v[132:133], v[150:151]
	s_nop 0
	v_add_f32_e32 v147, v133, v132
	v_mov_b32_e32 v132, v29
	v_mov_b32_e32 v133, v39
	v_pk_mul_f32 v[132:133], v[132:133], v[152:153]
	s_nop 0
	v_add_f32_e32 v132, v133, v132
	v_add_f32_e32 v133, v163, v162
	v_mov_b32_e32 v162, v31
	v_mov_b32_e32 v163, v41
	v_pk_mul_f32 v[162:163], v[162:163], v[154:155]
	v_cvt_pk_bf16_f32 v132, v147, v132
	s_nop 0
	v_add_f32_e32 v147, v163, v162
	v_add_co_u32_e32 v162, vcc, s18, v148
	v_cvt_pk_bf16_f32 v133, v133, v147
	s_movk_i32 s18, 0x3f4f
	s_nop 0
	v_addc_co_u32_e32 v163, vcc, 0, v149, vcc
	global_store_dwordx4 v[162:163], v[130:133], off sc1
	v_cmp_lt_i32_e32 vcc, s18, v144
	s_mov_b32 s18, 0x2c000
	v_mov_b32_e32 v130, v16
	v_mov_b32_e32 v131, v8
	v_pk_mul_f32 v[130:131], v[130:131], v[150:151]
	v_mov_b32_e32 v133, v10
	v_sub_f32_e32 v132, v130, v131
	v_mov_b32_e32 v130, v17
	v_mov_b32_e32 v131, v9
	v_pk_mul_f32 v[130:131], v[130:131], v[152:153]
	s_nop 0
	v_sub_f32_e32 v130, v130, v131
	v_cvt_pk_bf16_f32 v130, v132, v130
	v_mov_b32_e32 v132, v18
	v_pk_mul_f32 v[132:133], v[132:133], v[160:161]
	s_nop 0
	v_sub_f32_e32 v131, v132, v133
	v_mov_b32_e32 v132, v19
	v_mov_b32_e32 v133, v11
	v_pk_mul_f32 v[132:133], v[132:133], v[154:155]
	s_nop 0
	v_sub_f32_e32 v132, v132, v133
	v_cvt_pk_bf16_f32 v131, v131, v132
	v_mov_b32_e32 v132, v8
	v_mov_b32_e32 v133, v16
	v_pk_mul_f32 v[132:133], v[132:133], v[150:151]
	v_mov_b32_e32 v150, v10
	v_add_f32_e32 v147, v133, v132
	v_mov_b32_e32 v132, v9
	v_mov_b32_e32 v133, v17
	v_mov_b32_e32 v151, v18
	v_pk_mul_f32 v[132:133], v[132:133], v[152:153]
	v_pk_mul_f32 v[150:151], v[150:151], v[160:161]
	v_add_f32_e32 v132, v133, v132
	v_add_f32_e32 v133, v151, v150
	v_mov_b32_e32 v150, v11
	v_mov_b32_e32 v151, v19
	v_pk_mul_f32 v[150:151], v[150:151], v[154:155]
	v_cvt_pk_bf16_f32 v132, v147, v132
	s_nop 0
	v_add_f32_e32 v147, v151, v150
	v_cvt_pk_bf16_f32 v133, v133, v147
	global_store_dwordx4 v[162:163], v[130:133], off offset:256 sc1
	v_mov_b32_e32 v162, v14
	v_mov_b32_e32 v163, v22
	s_waitcnt vmcnt(2)
; __device__ __forceinline__ unsigned cvt_pk_bf16(float lo, float hi) { unsigned r; asm volatile("v_cvt_pk_bf16_f32 %0, %1, %2" : "=v"(r) : "v"(lo), "v"(hi)); return r; }
;     template <int LDC> __device__ __forceinline__ void store_rope(const f32x4 (&acc)[2][2][4][2], bf16_t* base, int row0, int wc, int fq) const {
;     ...
;             for (int m = 0; m < 4; ++m) { const int row = row0 + ai * HALF + m * 16; bf16_t* rowp = rp + (size_t)(ai * HALF + m * 16) * LDC;
;                 const int t = row & (SEQ - 1), pos = axis ? (t & 63) : (t >> 6);
;                 f32x4 cs0 = *(const f32x4*)(TAB + (pos * 32 + f0) * 2), cs1 = *(const f32x4*)(TAB + (pos * 32 + f0) * 2 + 4);
;                 if (row >= ML) { cs0 = (f32x4){1.f, 0.f, 1.f, 0.f}; cs1 = cs0; }
; #pragma unroll
;                 for (int bj = 0; bj < 2; ++bj) { const f32x4 x1 = acc[ai][bj][m][0], x2 = acc[ai][bj][m][1];
;                     u32x4 w;
;                     w.x = cvt_pk_bf16(x1[0] * cs0[0] - x2[0] * cs0[1], x1[1] * cs0[2] - x2[1] * cs0[3]);
;                     w.y = cvt_pk_bf16(x1[2] * cs1[0] - x2[2] * cs1[1], x1[3] * cs1[2] - x2[3] * cs1[3]);
;                     w.z = cvt_pk_bf16(x2[0] * cs0[0] + x1[0] * cs0[1], x2[1] * cs0[2] + x1[1] * cs0[3]);
;                     w.w = cvt_pk_bf16(x2[2] * cs1[0] + x1[2] * cs1[1], x2[3] * cs1[2] + x1[3] * cs1[3]);
;                     *(u32x4*)(rowp + bj * HALF) = w; } }
	s_nop 1
	v_mov_b32_e32 v130, v232
	v_mov_b32_e32 v131, v233
	v_mov_b32_e32 v132, v234
	v_mov_b32_e32 v133, v235
	v_mov_b32_e32 v150, v236
	v_mov_b32_e32 v151, v237
	v_mov_b32_e32 v152, v238
	v_mov_b32_e32 v153, v239
	s_nop 0
	v_cndmask_b32_e64 v161, v131, 0, vcc
	v_cndmask_b32_e64 v151, v151, 0, vcc
	v_cndmask_b32_e64 v150, v150, 1.0, vcc
	v_cndmask_b32_e64 v160, v130, 1.0, vcc
	v_mov_b32_e32 v130, v20
	v_mov_b32_e32 v131, v12
	v_pk_mul_f32 v[130:131], v[130:131], v[150:151]
	v_cndmask_b32_e64 v153, v153, 0, vcc
	v_cndmask_b32_e64 v152, v152, 1.0, vcc
	v_cndmask_b32_e64 v154, v132, 1.0, vcc
	v_sub_f32_e32 v132, v130, v131
	v_mov_b32_e32 v130, v21
	v_mov_b32_e32 v131, v13
	v_pk_mul_f32 v[130:131], v[130:131], v[152:153]
	v_cndmask_b32_e64 v155, v133, 0, vcc
	v_sub_f32_e32 v130, v130, v131
	v_cvt_pk_bf16_f32 v130, v132, v130
	v_mov_b32_e32 v132, v22
	v_mov_b32_e32 v133, v14
	v_pk_mul_f32 v[132:133], v[132:133], v[160:161]
	v_pk_mul_f32 v[162:163], v[162:163], v[160:161]
	v_sub_f32_e32 v131, v132, v133
	v_mov_b32_e32 v132, v23
	v_mov_b32_e32 v133, v15
	v_pk_mul_f32 v[132:133], v[132:133], v[154:155]
	v_add_co_u32_e32 v148, vcc, s18, v148
	v_sub_f32_e32 v132, v132, v133
	v_cvt_pk_bf16_f32 v131, v131, v132
	v_mov_b32_e32 v132, v12
	v_mov_b32_e32 v133, v20
	v_pk_mul_f32 v[132:133], v[132:133], v[150:151]
	v_addc_co_u32_e32 v149, vcc, 0, v149, vcc
	v_add_f32_e32 v145, v133, v132
	v_mov_b32_e32 v132, v13
	v_mov_b32_e32 v133, v21
	v_pk_mul_f32 v[132:133], v[132:133], v[152:153]
	s_nop 0
	v_add_f32_e32 v132, v133, v132
	v_add_f32_e32 v133, v163, v162
	v_mov_b32_e32 v162, v15
	v_mov_b32_e32 v163, v23
	v_pk_mul_f32 v[162:163], v[162:163], v[154:155]
	v_cvt_pk_bf16_f32 v132, v145, v132
	s_nop 0
	v_add_f32_e32 v145, v163, v162
	v_cvt_pk_bf16_f32 v133, v133, v145
	global_store_dwordx4 v[148:149], v[130:133], off sc1
	s_nop 1
	v_mov_b32_e32 v130, v4
	v_mov_b32_e32 v131, v0
	v_pk_mul_f32 v[130:131], v[130:131], v[150:151]
	v_mov_b32_e32 v133, v2
	v_sub_f32_e32 v132, v130, v131
	v_mov_b32_e32 v130, v5
	v_mov_b32_e32 v131, v1
	v_pk_mul_f32 v[130:131], v[130:131], v[152:153]
	s_nop 0
	v_sub_f32_e32 v130, v130, v131
	v_cvt_pk_bf16_f32 v130, v132, v130
	v_mov_b32_e32 v132, v6
	v_pk_mul_f32 v[132:133], v[132:133], v[160:161]
	s_nop 0
	v_sub_f32_e32 v131, v132, v133
	v_mov_b32_e32 v132, v7
	v_mov_b32_e32 v133, v3
	v_pk_mul_f32 v[132:133], v[132:133], v[154:155]
	s_nop 0
	v_sub_f32_e32 v132, v132, v133
	v_cvt_pk_bf16_f32 v131, v131, v132
	v_mov_b32_e32 v132, v0
	v_mov_b32_e32 v133, v4
	v_pk_mul_f32 v[132:133], v[132:133], v[150:151]
	v_mov_b32_e32 v150, v2
	v_add_f32_e32 v145, v133, v132
	v_mov_b32_e32 v132, v1
	v_mov_b32_e32 v133, v5
	v_mov_b32_e32 v151, v6
	v_pk_mul_f32 v[132:133], v[132:133], v[152:153]
	v_pk_mul_f32 v[150:151], v[150:151], v[160:161]
	v_add_f32_e32 v132, v133, v132
	v_add_f32_e32 v133, v151, v150
	v_mov_b32_e32 v150, v3
	v_mov_b32_e32 v151, v7
	v_pk_mul_f32 v[150:151], v[150:151], v[154:155]
	v_cvt_pk_bf16_f32 v132, v145, v132
	s_nop 0
	v_add_f32_e32 v145, v151, v150
	v_cvt_pk_bf16_f32 v133, v133, v145
	global_store_dwordx4 v[148:149], v[130:133], off offset:256 sc1

; __device__ __forceinline__ unsigned cvt_pk_bf16(float lo, float hi) { unsigned r; asm volatile("v_cvt_pk_bf16_f32 %0, %1, %2" : "=v"(r) : "v"(lo), "v"(hi)); return r; }
;     template <int LDC> __device__ __forceinline__ void store_rope(const f32x4 (&acc)[2][2][4][2], bf16_t* base, int row0, int wc, int fq) const {
;         bf16_t* rp = base + (size_t)row0 * LDC; const int axis = wc >> 1, f0 = 16 * (wc & 1) + 4 * fq;
; #pragma unroll
;         for (int ai = 0; ai < 2; ++ai)
; #pragma unroll
;             for (int m = 0; m < 4; ++m) { const int row = row0 + ai * HALF + m * 16; bf16_t* rowp = rp + (size_t)(ai * HALF + m * 16) * LDC;
;                 const int t = row & (SEQ - 1), pos = axis ? (t & 63) : (t >> 6);
;                 f32x4 cs0 = *(const f32x4*)(TAB + (pos * 32 + f0) * 2), cs1 = *(const f32x4*)(TAB + (pos * 32 + f0) * 2 + 4);
;                 if (row >= ML) { cs0 = (f32x4){1.f, 0.f, 1.f, 0.f}; cs1 = cs0; }
; #pragma unroll
;                 for (int bj = 0; bj < 2; ++bj) { const f32x4 x1 = acc[ai][bj][m][0], x2 = acc[ai][bj][m][1];
;                     u32x4 w;
;                     w.x = cvt_pk_bf16(x1[0] * cs0[0] - x2[0] * cs0[1], x1[1] * cs0[2] - x2[1] * cs0[3]);
;                     w.y = cvt_pk_bf16(x1[2] * cs1[0] - x2[2] * cs1[1], x1[3] * cs1[2] - x2[3] * cs1[3]);
;                     w.z = cvt_pk_bf16(x2[0] * cs0[0] + x1[0] * cs0[1], x2[1] * cs0[2] + x1[1] * cs0[3]);
;                     w.w = cvt_pk_bf16(x2[2] * cs1[0] + x1[2] * cs1[1], x2[3] * cs1[2] + x1[3] * cs1[3]);
;                     *(u32x4*)(rowp + bj * HALF) = w; } }
.LBB0_598:
	s_and_b64 vcc, exec, s[18:19]
	s_cbranch_vccz .LBB0_600
	s_lshl_b32 s18, s63, 9
	s_add_u32 s18, s16, s18
	s_addc_u32 s19, s17, 0
	v_ashrrev_i32_e32 v147, 31, v146
	v_lshl_add_u64 v[130:131], v[146:147], 1, s[18:19]
	v_ashrrev_i32_e32 v145, 31, v144
	s_lshr_b32 s18, s45, 6
	v_lshlrev_b64 v[132:133], 11, v[144:145]
	v_mov_b32_e32 v147, s18
	v_lshl_add_u64 v[148:149], v[130:131], 0, v[132:133]
	v_cndmask_b32_e64 v130, v159, v147, s[40:41]
	v_lshlrev_b32_e32 v130, 5, v130
	v_lshl_add_u32 v145, v167, 2, s39
	v_and_b32_e32 v130, 0x7e0, v130
	v_add_lshl_u32 v130, v130, v145, 1
	v_ashrrev_i32_e32 v131, 31, v130
	v_lshl_add_u64 v[130:131], v[130:131], 2, s[20:21]
	global_load_dwordx4 v[176:179], v[130:131], off offset:16
	s_nop 0
	global_load_dwordx4 v[130:133], v[130:131], off
	v_or_b32_e32 v248, 16, v144
	v_cndmask_b32_e64 v248, v248, v147, s[40:41]
	v_lshlrev_b32_e32 v248, 5, v248
	v_and_b32_e32 v248, 0x7e0, v248
	v_add_lshl_u32 v248, v248, v145, 1
	v_ashrrev_i32_e32 v249, 31, v248
	v_lshl_add_u64 v[250:251], v[248:249], 2, s[20:21]
	global_load_dwordx4 v[232:235], v[250:251], off offset:16
	global_load_dwordx4 v[236:239], v[250:251], off
	s_movk_i32 s18, 0x3fff
	v_cmp_lt_i32_e32 vcc, s18, v144
	v_mov_b32_e32 v161, v108
	s_movk_i32 s18, 0x3fef
	s_addk_i32 s45, 0x80
	v_mov_b32_e32 v163, v56
	s_waitcnt vmcnt(2)
	v_cndmask_b32_e64 v153, v177, 0, vcc
	v_cndmask_b32_e64 v155, v131, 0, vcc
	v_cndmask_b32_e64 v154, v130, 1.0, vcc
	v_mov_b32_e32 v130, v126
	v_mov_b32_e32 v131, v122
	v_pk_mul_f32 v[130:131], v[130:131], v[154:155]
	v_cndmask_b32_e64 v133, v133, 0, vcc
	v_cndmask_b32_e64 v132, v132, 1.0, vcc
	v_sub_f32_e32 v160, v130, v131
	v_mov_b32_e32 v130, v127
	v_mov_b32_e32 v131, v123
	v_pk_mul_f32 v[130:131], v[130:131], v[132:133]
	v_cndmask_b32_e64 v152, v176, 1.0, vcc
	v_sub_f32_e32 v130, v130, v131
	v_cvt_pk_bf16_f32 v176, v160, v130
	v_mov_b32_e32 v130, v128
	v_mov_b32_e32 v131, v124
	v_pk_mul_f32 v[130:131], v[130:131], v[152:153]
	v_cndmask_b32_e64 v151, v179, 0, vcc
	v_cndmask_b32_e64 v150, v178, 1.0, vcc
	v_sub_f32_e32 v160, v130, v131
	v_mov_b32_e32 v130, v129
	v_mov_b32_e32 v131, v125
	v_pk_mul_f32 v[130:131], v[130:131], v[150:151]
	v_cmp_lt_i32_e32 vcc, s18, v144
	v_sub_f32_e32 v130, v130, v131
	v_cvt_pk_bf16_f32 v177, v160, v130
	v_mov_b32_e32 v130, v122
	v_mov_b32_e32 v131, v126
	v_pk_mul_f32 v[130:131], v[130:131], v[154:155]
	s_movk_i32 s18, 0x7000
	v_add_f32_e32 v160, v131, v130
	v_mov_b32_e32 v130, v123
	v_mov_b32_e32 v131, v127
	v_pk_mul_f32 v[130:131], v[130:131], v[132:133]
	s_nop 0
	v_add_f32_e32 v130, v131, v130
	v_cvt_pk_bf16_f32 v178, v160, v130
	v_mov_b32_e32 v130, v124
	v_mov_b32_e32 v131, v128
	v_pk_mul_f32 v[130:131], v[130:131], v[152:153]
	s_nop 0
	v_add_f32_e32 v160, v131, v130
	v_mov_b32_e32 v130, v125
	v_mov_b32_e32 v131, v129
	v_pk_mul_f32 v[130:131], v[130:131], v[150:151]
	s_nop 0
	v_add_f32_e32 v130, v131, v130
	v_cvt_pk_bf16_f32 v179, v160, v130
	v_mov_b32_e32 v130, v114
	v_mov_b32_e32 v131, v106
	v_pk_mul_f32 v[130:131], v[130:131], v[154:155]
	global_store_dwordx4 v[148:149], v[176:179], off offset:-4096 sc1
	v_sub_f32_e32 v160, v130, v131
	v_mov_b32_e32 v130, v115
	v_mov_b32_e32 v131, v107
	v_pk_mul_f32 v[130:131], v[130:131], v[132:133]
	s_nop 0
	v_sub_f32_e32 v130, v130, v131
	v_cvt_pk_bf16_f32 v130, v160, v130
	v_mov_b32_e32 v160, v116
	v_pk_mul_f32 v[160:161], v[160:161], v[152:153]
	s_nop 0
	v_sub_f32_e32 v131, v160, v161
	v_mov_b32_e32 v160, v117
	v_mov_b32_e32 v161, v109
	v_pk_mul_f32 v[160:161], v[160:161], v[150:151]
	s_nop 0
	v_sub_f32_e32 v160, v160, v161
	v_cvt_pk_bf16_f32 v131, v131, v160
	v_mov_b32_e32 v160, v106
	v_mov_b32_e32 v161, v114
	v_pk_mul_f32 v[154:155], v[160:161], v[154:155]
	v_mov_b32_e32 v161, v90
	v_add_f32_e32 v160, v155, v154
	v_mov_b32_e32 v154, v107
	v_mov_b32_e32 v155, v115
	v_pk_mul_f32 v[132:133], v[154:155], v[132:133]
	v_mov_b32_e32 v154, v108
	v_mov_b32_e32 v155, v116
	v_pk_mul_f32 v[152:153], v[154:155], v[152:153]
	v_add_f32_e32 v132, v133, v132
	v_add_f32_e32 v133, v153, v152
	v_mov_b32_e32 v152, v109
	v_mov_b32_e32 v153, v117
	v_pk_mul_f32 v[150:151], v[152:153], v[150:151]
	v_cvt_pk_bf16_f32 v132, v160, v132
	v_mov_b32_e32 v154, v118
	v_add_f32_e32 v150, v151, v150
	v_cvt_pk_bf16_f32 v133, v133, v150
	global_store_dwordx4 v[148:149], v[130:133], off offset:-3840 sc1
	v_mov_b32_e32 v155, v110
	s_nop 0
	s_waitcnt vmcnt(2)
; __device__ __forceinline__ unsigned cvt_pk_bf16(float lo, float hi) { unsigned r; asm volatile("v_cvt_pk_bf16_f32 %0, %1, %2" : "=v"(r) : "v"(lo), "v"(hi)); return r; }
;     template <int LDC> __device__ __forceinline__ void store_rope(const f32x4 (&acc)[2][2][4][2], bf16_t* base, int row0, int wc, int fq) const {
;     ...
;             for (int m = 0; m < 4; ++m) { const int row = row0 + ai * HALF + m * 16; bf16_t* rowp = rp + (size_t)(ai * HALF + m * 16) * LDC;
;                 const int t = row & (SEQ - 1), pos = axis ? (t & 63) : (t >> 6);
;                 f32x4 cs0 = *(const f32x4*)(TAB + (pos * 32 + f0) * 2), cs1 = *(const f32x4*)(TAB + (pos * 32 + f0) * 2 + 4);
;                 if (row >= ML) { cs0 = (f32x4){1.f, 0.f, 1.f, 0.f}; cs1 = cs0; }
; #pragma unroll
;                 for (int bj = 0; bj < 2; ++bj) { const f32x4 x1 = acc[ai][bj][m][0], x2 = acc[ai][bj][m][1];
;                     u32x4 w;
;                     w.x = cvt_pk_bf16(x1[0] * cs0[0] - x2[0] * cs0[1], x1[1] * cs0[2] - x2[1] * cs0[3]);
;                     w.y = cvt_pk_bf16(x1[2] * cs1[0] - x2[2] * cs1[1], x1[3] * cs1[2] - x2[3] * cs1[3]);
;                     w.z = cvt_pk_bf16(x2[0] * cs0[0] + x1[0] * cs0[1], x2[1] * cs0[2] + x1[1] * cs0[3]);
;                     w.w = cvt_pk_bf16(x2[2] * cs1[0] + x1[2] * cs1[1], x2[3] * cs1[2] + x1[3] * cs1[3]);
;                     *(u32x4*)(rowp + bj * HALF) = w; } }
	s_nop 1
	v_mov_b32_e32 v176, v232
	v_mov_b32_e32 v177, v233
	v_mov_b32_e32 v178, v234
	v_mov_b32_e32 v179, v235
	v_mov_b32_e32 v130, v236
	v_mov_b32_e32 v131, v237
	v_mov_b32_e32 v132, v238
	v_mov_b32_e32 v133, v239
	v_or_b32_e32 v248, 32, v144
	v_cndmask_b32_e64 v248, v248, v147, s[40:41]
	v_lshlrev_b32_e32 v248, 5, v248
	v_and_b32_e32 v248, 0x7e0, v248
	v_add_lshl_u32 v248, v248, v145, 1
	v_ashrrev_i32_e32 v249, 31, v248
	v_lshl_add_u64 v[250:251], v[248:249], 2, s[20:21]
	global_load_dwordx4 v[232:235], v[250:251], off offset:16
	global_load_dwordx4 v[236:239], v[250:251], off
	s_nop 0
	v_cndmask_b32_e64 v151, v177, 0, vcc
	v_cndmask_b32_e64 v153, v131, 0, vcc
	v_cndmask_b32_e64 v152, v130, 1.0, vcc
	v_pk_mul_f32 v[154:155], v[154:155], v[152:153]
	v_cndmask_b32_e64 v133, v133, 0, vcc
	v_cndmask_b32_e64 v132, v132, 1.0, vcc
	v_sub_f32_e32 v160, v154, v155
	v_mov_b32_e32 v154, v119
	v_mov_b32_e32 v155, v111
	v_pk_mul_f32 v[154:155], v[154:155], v[132:133]
	v_cndmask_b32_e64 v150, v176, 1.0, vcc
	v_sub_f32_e32 v154, v154, v155
	v_cvt_pk_bf16_f32 v176, v160, v154
	v_mov_b32_e32 v154, v120
	v_mov_b32_e32 v155, v112
	v_pk_mul_f32 v[154:155], v[154:155], v[150:151]
	v_cndmask_b32_e64 v131, v179, 0, vcc
	v_cndmask_b32_e64 v130, v178, 1.0, vcc
	v_sub_f32_e32 v160, v154, v155
	v_mov_b32_e32 v154, v121
	v_mov_b32_e32 v155, v113
	v_pk_mul_f32 v[154:155], v[154:155], v[130:131]
	s_nop 0
	v_sub_f32_e32 v154, v154, v155
	v_cvt_pk_bf16_f32 v177, v160, v154
	v_mov_b32_e32 v154, v110
	v_mov_b32_e32 v155, v118
	v_pk_mul_f32 v[154:155], v[154:155], v[152:153]
	s_nop 0
	v_add_f32_e32 v160, v155, v154
	v_mov_b32_e32 v154, v111
	v_mov_b32_e32 v155, v119
	v_pk_mul_f32 v[154:155], v[154:155], v[132:133]
	s_nop 0
	v_add_f32_e32 v154, v155, v154
	v_cvt_pk_bf16_f32 v178, v160, v154
	v_mov_b32_e32 v154, v112
	v_mov_b32_e32 v155, v120
	v_pk_mul_f32 v[154:155], v[154:155], v[150:151]
	s_nop 0
	v_add_f32_e32 v160, v155, v154
	v_mov_b32_e32 v154, v113
	v_mov_b32_e32 v155, v121
	v_pk_mul_f32 v[154:155], v[154:155], v[130:131]
	s_nop 0
	v_add_f32_e32 v154, v155, v154
	v_cvt_pk_bf16_f32 v179, v160, v154
	v_mov_b32_e32 v160, v98
	v_pk_mul_f32 v[160:161], v[160:161], v[152:153]
	v_add_co_u32_e32 v154, vcc, s18, v148
	v_sub_f32_e32 v162, v160, v161
	v_mov_b32_e32 v160, v99
	v_mov_b32_e32 v161, v91
	v_pk_mul_f32 v[160:161], v[160:161], v[132:133]
	v_addc_co_u32_e32 v155, vcc, 0, v149, vcc
	v_sub_f32_e32 v160, v160, v161
	global_store_dwordx4 v[154:155], v[176:179], off sc1
	v_mov_b32_e32 v161, v92
	s_movk_i32 s18, 0x3fdf
	v_cvt_pk_bf16_f32 v176, v162, v160
	v_mov_b32_e32 v160, v100
	v_pk_mul_f32 v[160:161], v[160:161], v[150:151]
	v_cmp_lt_i32_e32 vcc, s18, v144
	v_sub_f32_e32 v162, v160, v161
	v_mov_b32_e32 v160, v101
	v_mov_b32_e32 v161, v93
	v_pk_mul_f32 v[160:161], v[160:161], v[130:131]
	s_mov_b32 s18, 0xf000
	v_sub_f32_e32 v160, v160, v161
	v_cvt_pk_bf16_f32 v177, v162, v160
	v_mov_b32_e32 v160, v90
	v_mov_b32_e32 v161, v98
	v_pk_mul_f32 v[152:153], v[160:161], v[152:153]
	v_mov_b32_e32 v161, v74
	v_add_f32_e32 v160, v153, v152
	v_mov_b32_e32 v152, v91
	v_mov_b32_e32 v153, v99
	v_pk_mul_f32 v[132:133], v[152:153], v[132:133]
	s_nop 0
	v_add_f32_e32 v132, v133, v132
	v_cvt_pk_bf16_f32 v178, v160, v132
	v_mov_b32_e32 v132, v92
	v_mov_b32_e32 v133, v100
	v_pk_mul_f32 v[132:133], v[132:133], v[150:151]
	s_nop 0
	v_add_f32_e32 v150, v133, v132
	v_mov_b32_e32 v132, v93
	v_mov_b32_e32 v133, v101
	v_pk_mul_f32 v[130:131], v[132:133], v[130:131]
	s_nop 0
	v_add_f32_e32 v130, v131, v130
	v_cvt_pk_bf16_f32 v179, v150, v130
	global_store_dwordx4 v[154:155], v[176:179], off offset:256 sc1
	s_waitcnt vmcnt(2)
	s_nop 1
	v_mov_b32_e32 v176, v232
	v_mov_b32_e32 v177, v233
	v_mov_b32_e32 v178, v234
	v_mov_b32_e32 v179, v235
	v_mov_b32_e32 v130, v236
	v_mov_b32_e32 v131, v237
	v_mov_b32_e32 v132, v238
	v_mov_b32_e32 v133, v239
	v_or_b32_e32 v248, 48, v144
	v_cndmask_b32_e64 v248, v248, v147, s[40:41]
	v_lshlrev_b32_e32 v248, 5, v248
	v_and_b32_e32 v248, 0x7e0, v248
	v_add_lshl_u32 v248, v248, v145, 1
	v_ashrrev_i32_e32 v249, 31, v248
	v_lshl_add_u64 v[250:251], v[248:249], 2, s[20:21]
	global_load_dwordx4 v[232:235], v[250:251], off offset:16
	global_load_dwordx4 v[236:239], v[250:251], off
	s_nop 0
	v_mov_b32_e32 v154, v102
	v_mov_b32_e32 v155, v94
	v_cndmask_b32_e64 v151, v177, 0, vcc
	v_cndmask_b32_e64 v153, v131, 0, vcc
	v_cndmask_b32_e64 v152, v130, 1.0, vcc
	v_pk_mul_f32 v[154:155], v[154:155], v[152:153]
	v_cndmask_b32_e64 v133, v133, 0, vcc
	v_cndmask_b32_e64 v132, v132, 1.0, vcc
	v_sub_f32_e32 v160, v154, v155
	v_mov_b32_e32 v154, v103
	v_mov_b32_e32 v155, v95
	v_pk_mul_f32 v[154:155], v[154:155], v[132:133]
	v_cndmask_b32_e64 v150, v176, 1.0, vcc
	v_sub_f32_e32 v154, v154, v155
	v_cvt_pk_bf16_f32 v176, v160, v154
	v_mov_b32_e32 v154, v104
	v_mov_b32_e32 v155, v96
	v_pk_mul_f32 v[154:155], v[154:155], v[150:151]
	v_cndmask_b32_e64 v131, v179, 0, vcc
	v_cndmask_b32_e64 v130, v178, 1.0, vcc
	v_sub_f32_e32 v160, v154, v155
	v_mov_b32_e32 v154, v105
	v_mov_b32_e32 v155, v97
	v_pk_mul_f32 v[154:155], v[154:155], v[130:131]
	s_nop 0
	v_sub_f32_e32 v154, v154, v155
	v_cvt_pk_bf16_f32 v177, v160, v154
	v_mov_b32_e32 v154, v94
	v_mov_b32_e32 v155, v102
	v_pk_mul_f32 v[154:155], v[154:155], v[152:153]
	s_nop 0
	v_add_f32_e32 v160, v155, v154
	v_mov_b32_e32 v154, v95
	v_mov_b32_e32 v155, v103
	v_pk_mul_f32 v[154:155], v[154:155], v[132:133]
	s_nop 0
	v_add_f32_e32 v154, v155, v154
	v_cvt_pk_bf16_f32 v178, v160, v154
	v_mov_b32_e32 v154, v96
	v_mov_b32_e32 v155, v104
	v_pk_mul_f32 v[154:155], v[154:155], v[150:151]
	s_nop 0
	v_add_f32_e32 v160, v155, v154
	v_mov_b32_e32 v154, v97
; __device__ __forceinline__ unsigned cvt_pk_bf16(float lo, float hi) { unsigned r; asm volatile("v_cvt_pk_bf16_f32 %0, %1, %2" : "=v"(r) : "v"(lo), "v"(hi)); return r; }
;     template <int LDC> __device__ __forceinline__ void store_rope(const f32x4 (&acc)[2][2][4][2], bf16_t* base, int row0, int wc, int fq) const {
;     ...
;             for (int m = 0; m < 4; ++m) { const int row = row0 + ai * HALF + m * 16; bf16_t* rowp = rp + (size_t)(ai * HALF + m * 16) * LDC;
;                 const int t = row & (SEQ - 1), pos = axis ? (t & 63) : (t >> 6);
;                 f32x4 cs0 = *(const f32x4*)(TAB + (pos * 32 + f0) * 2), cs1 = *(const f32x4*)(TAB + (pos * 32 + f0) * 2 + 4);
;                 if (row >= ML) { cs0 = (f32x4){1.f, 0.f, 1.f, 0.f}; cs1 = cs0; }
; #pragma unroll
;                 for (int bj = 0; bj < 2; ++bj) { const f32x4 x1 = acc[ai][bj][m][0], x2 = acc[ai][bj][m][1];
;                     u32x4 w;
;                     w.x = cvt_pk_bf16(x1[0] * cs0[0] - x2[0] * cs0[1], x1[1] * cs0[2] - x2[1] * cs0[3]);
;                     w.y = cvt_pk_bf16(x1[2] * cs1[0] - x2[2] * cs1[1], x1[3] * cs1[2] - x2[3] * cs1[3]);
;                     w.z = cvt_pk_bf16(x2[0] * cs0[0] + x1[0] * cs0[1], x2[1] * cs0[2] + x1[1] * cs0[3]);
;                     w.w = cvt_pk_bf16(x2[2] * cs1[0] + x1[2] * cs1[1], x2[3] * cs1[2] + x1[3] * cs1[3]);
;                     *(u32x4*)(rowp + bj * HALF) = w; } }
	v_mov_b32_e32 v155, v105
	v_pk_mul_f32 v[154:155], v[154:155], v[130:131]
	s_nop 0
	v_add_f32_e32 v154, v155, v154
	v_cvt_pk_bf16_f32 v179, v160, v154
	v_mov_b32_e32 v160, v82
	v_pk_mul_f32 v[160:161], v[160:161], v[152:153]
	v_add_co_u32_e32 v154, vcc, s18, v148
	v_sub_f32_e32 v162, v160, v161
	v_mov_b32_e32 v160, v83
	v_mov_b32_e32 v161, v75
	v_pk_mul_f32 v[160:161], v[160:161], v[132:133]
	v_addc_co_u32_e32 v155, vcc, 0, v149, vcc
	v_sub_f32_e32 v160, v160, v161
	global_store_dwordx4 v[154:155], v[176:179], off sc1
	v_mov_b32_e32 v161, v76
	s_movk_i32 s18, 0x3fcf
	v_cvt_pk_bf16_f32 v176, v162, v160
	v_mov_b32_e32 v160, v84
	v_pk_mul_f32 v[160:161], v[160:161], v[150:151]
	v_cmp_lt_i32_e32 vcc, s18, v144
	v_sub_f32_e32 v162, v160, v161
	v_mov_b32_e32 v160, v85
	v_mov_b32_e32 v161, v77
	v_pk_mul_f32 v[160:161], v[160:161], v[130:131]
	s_mov_b32 s18, 0x17000
	v_sub_f32_e32 v160, v160, v161
	v_cvt_pk_bf16_f32 v177, v162, v160
	v_mov_b32_e32 v160, v74
	v_mov_b32_e32 v161, v82
	v_pk_mul_f32 v[152:153], v[160:161], v[152:153]
	v_mov_b32_e32 v161, v66
	v_add_f32_e32 v160, v153, v152
	v_mov_b32_e32 v152, v75
	v_mov_b32_e32 v153, v83
	v_pk_mul_f32 v[132:133], v[152:153], v[132:133]
	v_mov_b32_e32 v162, v48
	v_add_f32_e32 v132, v133, v132
	v_cvt_pk_bf16_f32 v178, v160, v132
	v_mov_b32_e32 v132, v76
	v_mov_b32_e32 v133, v84
	v_pk_mul_f32 v[132:133], v[132:133], v[150:151]
	v_mov_b32_e32 v160, v70
	v_add_f32_e32 v150, v133, v132
	v_mov_b32_e32 v132, v77
	v_mov_b32_e32 v133, v85
	v_pk_mul_f32 v[130:131], v[132:133], v[130:131]
	s_nop 0
	v_add_f32_e32 v130, v131, v130
	v_cvt_pk_bf16_f32 v179, v150, v130
	global_store_dwordx4 v[154:155], v[176:179], off offset:256 sc1
	s_waitcnt vmcnt(2)
	s_nop 1
	v_mov_b32_e32 v176, v232
	v_mov_b32_e32 v177, v233
	v_mov_b32_e32 v178, v234
	v_mov_b32_e32 v179, v235
	v_mov_b32_e32 v130, v236
	v_mov_b32_e32 v131, v237
	v_mov_b32_e32 v132, v238
	v_mov_b32_e32 v133, v239
	s_lshr_b32 s100, s45, 6
	v_mov_b32_e32 v248, s100
	v_cndmask_b32_e64 v248, v159, v248, s[40:41]
	v_lshlrev_b32_e32 v248, 5, v248
	v_and_b32_e32 v248, 0x7e0, v248
	v_add_lshl_u32 v248, v248, v145, 1
	v_ashrrev_i32_e32 v249, 31, v248
	v_lshl_add_u64 v[250:251], v[248:249], 2, s[20:21]
	global_load_dwordx4 v[232:235], v[250:251], off offset:16
	global_load_dwordx4 v[236:239], v[250:251], off
	s_nop 0
	v_mov_b32_e32 v154, v86
	v_mov_b32_e32 v155, v78
	v_cndmask_b32_e64 v151, v177, 0, vcc
	v_cndmask_b32_e64 v153, v131, 0, vcc
	v_cndmask_b32_e64 v152, v130, 1.0, vcc
	v_pk_mul_f32 v[154:155], v[154:155], v[152:153]
	v_cndmask_b32_e64 v133, v133, 0, vcc
	v_cndmask_b32_e64 v132, v132, 1.0, vcc
	v_sub_f32_e32 v147, v154, v155
	v_mov_b32_e32 v154, v87
	v_mov_b32_e32 v155, v79
	v_pk_mul_f32 v[154:155], v[154:155], v[132:133]
	v_cndmask_b32_e64 v150, v176, 1.0, vcc
	v_sub_f32_e32 v154, v154, v155
	v_cvt_pk_bf16_f32 v176, v147, v154
	v_mov_b32_e32 v154, v88
	v_mov_b32_e32 v155, v80
	v_pk_mul_f32 v[154:155], v[154:155], v[150:151]
	v_cndmask_b32_e64 v131, v179, 0, vcc
	v_cndmask_b32_e64 v130, v178, 1.0, vcc
	v_sub_f32_e32 v147, v154, v155
	v_mov_b32_e32 v154, v89
	v_mov_b32_e32 v155, v81
	v_pk_mul_f32 v[154:155], v[154:155], v[130:131]
	v_pk_mul_f32 v[160:161], v[160:161], v[152:153]
	v_sub_f32_e32 v154, v154, v155
	v_cvt_pk_bf16_f32 v177, v147, v154
	v_mov_b32_e32 v154, v78
	v_mov_b32_e32 v155, v86
	v_pk_mul_f32 v[154:155], v[154:155], v[152:153]
	s_nop 0
	v_add_f32_e32 v147, v155, v154
	v_mov_b32_e32 v154, v79
	v_mov_b32_e32 v155, v87
	v_pk_mul_f32 v[154:155], v[154:155], v[132:133]
	s_nop 0
	v_add_f32_e32 v154, v155, v154
	v_cvt_pk_bf16_f32 v178, v147, v154
	v_mov_b32_e32 v154, v80
	v_mov_b32_e32 v155, v88
	v_pk_mul_f32 v[154:155], v[154:155], v[150:151]
	s_nop 0
	v_add_f32_e32 v147, v155, v154
	v_mov_b32_e32 v154, v81
	v_mov_b32_e32 v155, v89
	v_pk_mul_f32 v[154:155], v[154:155], v[130:131]
	s_nop 0
	v_add_f32_e32 v154, v155, v154
	v_cvt_pk_bf16_f32 v179, v147, v154
	v_sub_f32_e32 v147, v160, v161
	v_mov_b32_e32 v160, v71
	v_mov_b32_e32 v161, v67
	v_add_co_u32_e32 v154, vcc, s18, v148
	v_pk_mul_f32 v[160:161], v[160:161], v[132:133]
	s_nop 0
	v_addc_co_u32_e32 v155, vcc, 0, v149, vcc
	v_sub_f32_e32 v160, v160, v161
	global_store_dwordx4 v[154:155], v[176:179], off sc1
	v_mov_b32_e32 v161, v68
	s_lshr_b32 s18, s45, 6
	v_cvt_pk_bf16_f32 v176, v147, v160
	v_mov_b32_e32 v160, v72
	v_pk_mul_f32 v[160:161], v[160:161], v[150:151]
	s_nop 0
	v_sub_f32_e32 v147, v160, v161
	v_mov_b32_e32 v160, v73
	v_mov_b32_e32 v161, v69
	v_pk_mul_f32 v[160:161], v[160:161], v[130:131]
	s_nop 0
	v_sub_f32_e32 v160, v160, v161
	v_cvt_pk_bf16_f32 v177, v147, v160
	v_mov_b32_e32 v160, v66
	v_mov_b32_e32 v161, v70
	v_pk_mul_f32 v[152:153], v[160:161], v[152:153]
	v_mov_b32_e32 v160, v50
	v_add_f32_e32 v147, v153, v152
	v_mov_b32_e32 v152, v67
	v_mov_b32_e32 v153, v71
	v_pk_mul_f32 v[132:133], v[152:153], v[132:133]
	v_mov_b32_e32 v161, v42
	v_add_f32_e32 v132, v133, v132
	v_cvt_pk_bf16_f32 v178, v147, v132
	v_mov_b32_e32 v132, v68
	v_mov_b32_e32 v133, v72
	v_pk_mul_f32 v[132:133], v[132:133], v[150:151]
	s_nop 0
	v_add_f32_e32 v147, v133, v132
	v_mov_b32_e32 v132, v69
	v_mov_b32_e32 v133, v73
	v_pk_mul_f32 v[130:131], v[132:133], v[130:131]
	s_nop 0
	v_add_f32_e32 v130, v131, v130
	v_cvt_pk_bf16_f32 v179, v147, v130
	global_store_dwordx4 v[154:155], v[176:179], off offset:256 sc1
	s_waitcnt vmcnt(2)
; __device__ __forceinline__ unsigned cvt_pk_bf16(float lo, float hi) { unsigned r; asm volatile("v_cvt_pk_bf16_f32 %0, %1, %2" : "=v"(r) : "v"(lo), "v"(hi)); return r; }
;     template <int LDC> __device__ __forceinline__ void store_rope(const f32x4 (&acc)[2][2][4][2], bf16_t* base, int row0, int wc, int fq) const {
;     ...
;             for (int m = 0; m < 4; ++m) { const int row = row0 + ai * HALF + m * 16; bf16_t* rowp = rp + (size_t)(ai * HALF + m * 16) * LDC;
;                 const int t = row & (SEQ - 1), pos = axis ? (t & 63) : (t >> 6);
;                 f32x4 cs0 = *(const f32x4*)(TAB + (pos * 32 + f0) * 2), cs1 = *(const f32x4*)(TAB + (pos * 32 + f0) * 2 + 4);
;                 if (row >= ML) { cs0 = (f32x4){1.f, 0.f, 1.f, 0.f}; cs1 = cs0; }
; #pragma unroll
;                 for (int bj = 0; bj < 2; ++bj) { const f32x4 x1 = acc[ai][bj][m][0], x2 = acc[ai][bj][m][1];
;                     u32x4 w;
;                     w.x = cvt_pk_bf16(x1[0] * cs0[0] - x2[0] * cs0[1], x1[1] * cs0[2] - x2[1] * cs0[3]);
;                     w.y = cvt_pk_bf16(x1[2] * cs1[0] - x2[2] * cs1[1], x1[3] * cs1[2] - x2[3] * cs1[3]);
;                     w.z = cvt_pk_bf16(x2[0] * cs0[0] + x1[0] * cs0[1], x2[1] * cs0[2] + x1[1] * cs0[3]);
;                     w.w = cvt_pk_bf16(x2[2] * cs1[0] + x1[2] * cs1[1], x2[3] * cs1[2] + x1[3] * cs1[3]);
;                     *(u32x4*)(rowp + bj * HALF) = w; } }
	s_nop 1
	v_mov_b32_e32 v176, v232
	v_mov_b32_e32 v177, v233
	v_mov_b32_e32 v178, v234
	v_mov_b32_e32 v179, v235
	v_mov_b32_e32 v130, v236
	v_mov_b32_e32 v131, v237
	v_mov_b32_e32 v132, v238
	v_mov_b32_e32 v133, v239
	v_add_u32_e32 v248, 0x90, v144
	v_lshrrev_b32_e32 v249, 6, v248
	v_cndmask_b32_e64 v248, v248, v249, s[40:41]
	v_lshlrev_b32_e32 v248, 5, v248
	v_and_b32_e32 v248, 0x7e0, v248
	v_add_lshl_u32 v248, v248, v145, 1
	v_ashrrev_i32_e32 v249, 31, v248
	v_lshl_add_u64 v[250:251], v[248:249], 2, s[20:21]
	global_load_dwordx4 v[232:235], v[250:251], off offset:16
	global_load_dwordx4 v[236:239], v[250:251], off
	s_nop 0
	s_movk_i32 s18, 0x3f7f
	v_cmp_lt_i32_e32 vcc, s18, v144
	v_mov_b32_e32 v154, v62
	v_mov_b32_e32 v155, v58
	s_mov_b32 s18, 0x3f000
	v_cndmask_b32_e64 v151, v177, 0, vcc
	v_cndmask_b32_e64 v153, v131, 0, vcc
	v_cndmask_b32_e64 v152, v130, 1.0, vcc
	v_pk_mul_f32 v[154:155], v[154:155], v[152:153]
	v_cndmask_b32_e64 v133, v133, 0, vcc
	v_cndmask_b32_e64 v132, v132, 1.0, vcc
	v_sub_f32_e32 v147, v154, v155
	v_mov_b32_e32 v154, v63
	v_mov_b32_e32 v155, v59
	v_pk_mul_f32 v[154:155], v[154:155], v[132:133]
	v_cndmask_b32_e64 v150, v176, 1.0, vcc
	v_sub_f32_e32 v154, v154, v155
	v_cvt_pk_bf16_f32 v176, v147, v154
	v_mov_b32_e32 v154, v64
	v_mov_b32_e32 v155, v60
	v_pk_mul_f32 v[154:155], v[154:155], v[150:151]
	v_cndmask_b32_e64 v131, v179, 0, vcc
	v_cndmask_b32_e64 v130, v178, 1.0, vcc
	v_sub_f32_e32 v147, v154, v155
	v_mov_b32_e32 v154, v65
	v_mov_b32_e32 v155, v61
	v_pk_mul_f32 v[154:155], v[154:155], v[130:131]
	v_pk_mul_f32 v[160:161], v[160:161], v[152:153]
	v_sub_f32_e32 v154, v154, v155
	v_cvt_pk_bf16_f32 v177, v147, v154
	v_mov_b32_e32 v154, v58
	v_mov_b32_e32 v155, v62
	v_pk_mul_f32 v[154:155], v[154:155], v[152:153]
	s_nop 0
	v_add_f32_e32 v147, v155, v154
	v_mov_b32_e32 v154, v59
	v_mov_b32_e32 v155, v63
	v_pk_mul_f32 v[154:155], v[154:155], v[132:133]
	s_nop 0
	v_add_f32_e32 v154, v155, v154
	v_cvt_pk_bf16_f32 v178, v147, v154
	v_mov_b32_e32 v154, v60
	v_mov_b32_e32 v155, v64
	v_pk_mul_f32 v[154:155], v[154:155], v[150:151]
	s_nop 0
	v_add_f32_e32 v147, v155, v154
	v_mov_b32_e32 v154, v61
	v_mov_b32_e32 v155, v65
	v_pk_mul_f32 v[154:155], v[154:155], v[130:131]
	s_nop 0
	v_add_f32_e32 v154, v155, v154
	v_cvt_pk_bf16_f32 v179, v147, v154
	v_sub_f32_e32 v147, v160, v161
	v_mov_b32_e32 v160, v51
	v_mov_b32_e32 v161, v43
	v_pk_mul_f32 v[160:161], v[160:161], v[132:133]
	v_add_co_u32_e32 v154, vcc, s18, v148
	v_sub_f32_e32 v159, v160, v161
	v_mov_b32_e32 v160, v52
	v_mov_b32_e32 v161, v44
	v_addc_co_u32_e32 v155, vcc, 0, v149, vcc
	v_pk_mul_f32 v[160:161], v[160:161], v[150:151]
	global_store_dwordx4 v[154:155], v[176:179], off sc1
	s_movk_i32 s18, 0x3f6f
	v_cmp_lt_i32_e32 vcc, s18, v144
	v_cvt_pk_bf16_f32 v176, v147, v159
	v_sub_f32_e32 v147, v160, v161
	v_mov_b32_e32 v160, v53
	v_mov_b32_e32 v161, v45
	v_pk_mul_f32 v[160:161], v[160:161], v[130:131]
	s_mov_b32 s18, 0x47000
	v_sub_f32_e32 v159, v160, v161
	v_mov_b32_e32 v160, v42
	v_mov_b32_e32 v161, v50
	v_pk_mul_f32 v[152:153], v[160:161], v[152:153]
	v_cvt_pk_bf16_f32 v177, v147, v159
	s_nop 0
	v_add_f32_e32 v147, v153, v152
	v_mov_b32_e32 v152, v43
	v_mov_b32_e32 v153, v51
	v_pk_mul_f32 v[132:133], v[152:153], v[132:133]
	s_nop 0
	v_add_f32_e32 v132, v133, v132
	v_cvt_pk_bf16_f32 v178, v147, v132
	v_mov_b32_e32 v132, v44
	v_mov_b32_e32 v133, v52
	v_pk_mul_f32 v[132:133], v[132:133], v[150:151]
	s_nop 0
	v_add_f32_e32 v147, v133, v132
	v_mov_b32_e32 v132, v45
	v_mov_b32_e32 v133, v53
	v_pk_mul_f32 v[130:131], v[132:133], v[130:131]
	s_nop 0
	v_add_f32_e32 v130, v131, v130
	v_cvt_pk_bf16_f32 v179, v147, v130
	global_store_dwordx4 v[154:155], v[176:179], off offset:256 sc1
	s_waitcnt vmcnt(2)
	s_nop 1
	v_mov_b32_e32 v130, v232
	v_mov_b32_e32 v131, v233
	v_mov_b32_e32 v132, v234
	v_mov_b32_e32 v133, v235
	v_mov_b32_e32 v150, v236
	v_mov_b32_e32 v151, v237
	v_mov_b32_e32 v152, v238
	v_mov_b32_e32 v153, v239
	v_add_u32_e32 v248, 0xa0, v144
	v_lshrrev_b32_e32 v249, 6, v248
	v_cndmask_b32_e64 v248, v248, v249, s[40:41]
	v_lshlrev_b32_e32 v248, 5, v248
	v_and_b32_e32 v248, 0x7e0, v248
	v_add_lshl_u32 v248, v248, v145, 1
	v_ashrrev_i32_e32 v249, 31, v248
	v_lshl_add_u64 v[250:251], v[248:249], 2, s[20:21]
	global_load_dwordx4 v[232:235], v[250:251], off offset:16
	global_load_dwordx4 v[236:239], v[250:251], off
	s_nop 0
	v_cndmask_b32_e64 v161, v131, 0, vcc
	v_cndmask_b32_e64 v151, v151, 0, vcc
	v_cndmask_b32_e64 v150, v150, 1.0, vcc
	v_cndmask_b32_e64 v160, v130, 1.0, vcc
	v_mov_b32_e32 v130, v54
	v_mov_b32_e32 v131, v46
	v_pk_mul_f32 v[130:131], v[130:131], v[150:151]
	v_cndmask_b32_e64 v153, v153, 0, vcc
	v_cndmask_b32_e64 v152, v152, 1.0, vcc
	v_cndmask_b32_e64 v154, v132, 1.0, vcc
	v_sub_f32_e32 v132, v130, v131
	v_mov_b32_e32 v130, v55
	v_mov_b32_e32 v131, v47
	v_pk_mul_f32 v[130:131], v[130:131], v[152:153]
	v_cndmask_b32_e64 v155, v133, 0, vcc
	v_sub_f32_e32 v130, v130, v131
	v_cvt_pk_bf16_f32 v130, v132, v130
	v_mov_b32_e32 v132, v56
	v_mov_b32_e32 v133, v48
	v_pk_mul_f32 v[132:133], v[132:133], v[160:161]
	v_pk_mul_f32 v[162:163], v[162:163], v[160:161]
	v_sub_f32_e32 v131, v132, v133
	v_mov_b32_e32 v132, v57
	v_mov_b32_e32 v133, v49
	v_pk_mul_f32 v[132:133], v[132:133], v[154:155]
	s_nop 0
	v_sub_f32_e32 v132, v132, v133
	v_cvt_pk_bf16_f32 v131, v131, v132
	v_mov_b32_e32 v132, v46
	v_mov_b32_e32 v133, v54
	v_pk_mul_f32 v[132:133], v[132:133], v[150:151]
	s_nop 0
	v_add_f32_e32 v147, v133, v132
	v_mov_b32_e32 v132, v47
	v_mov_b32_e32 v133, v55
	v_pk_mul_f32 v[132:133], v[132:133], v[152:153]
	s_nop 0
	v_add_f32_e32 v132, v133, v132
	v_add_f32_e32 v133, v163, v162
; __device__ __forceinline__ unsigned cvt_pk_bf16(float lo, float hi) { unsigned r; asm volatile("v_cvt_pk_bf16_f32 %0, %1, %2" : "=v"(r) : "v"(lo), "v"(hi)); return r; }
;     template <int LDC> __device__ __forceinline__ void store_rope(const f32x4 (&acc)[2][2][4][2], bf16_t* base, int row0, int wc, int fq) const {
;     ...
;             for (int m = 0; m < 4; ++m) { const int row = row0 + ai * HALF + m * 16; bf16_t* rowp = rp + (size_t)(ai * HALF + m * 16) * LDC;
;                 const int t = row & (SEQ - 1), pos = axis ? (t & 63) : (t >> 6);
;                 f32x4 cs0 = *(const f32x4*)(TAB + (pos * 32 + f0) * 2), cs1 = *(const f32x4*)(TAB + (pos * 32 + f0) * 2 + 4);
;                 if (row >= ML) { cs0 = (f32x4){1.f, 0.f, 1.f, 0.f}; cs1 = cs0; }
; #pragma unroll
;                 for (int bj = 0; bj < 2; ++bj) { const f32x4 x1 = acc[ai][bj][m][0], x2 = acc[ai][bj][m][1];
;                     u32x4 w;
;                     w.x = cvt_pk_bf16(x1[0] * cs0[0] - x2[0] * cs0[1], x1[1] * cs0[2] - x2[1] * cs0[3]);
;                     w.y = cvt_pk_bf16(x1[2] * cs1[0] - x2[2] * cs1[1], x1[3] * cs1[2] - x2[3] * cs1[3]);
;                     w.z = cvt_pk_bf16(x2[0] * cs0[0] + x1[0] * cs0[1], x2[1] * cs0[2] + x1[1] * cs0[3]);
;                     w.w = cvt_pk_bf16(x2[2] * cs1[0] + x1[2] * cs1[1], x2[3] * cs1[2] + x1[3] * cs1[3]);
;                     *(u32x4*)(rowp + bj * HALF) = w; } }
	v_mov_b32_e32 v162, v49
	v_mov_b32_e32 v163, v57
	v_pk_mul_f32 v[162:163], v[162:163], v[154:155]
	v_cvt_pk_bf16_f32 v132, v147, v132
	s_nop 0
	v_add_f32_e32 v147, v163, v162
	v_add_co_u32_e32 v162, vcc, s18, v148
	v_cvt_pk_bf16_f32 v133, v133, v147
	s_movk_i32 s18, 0x3f5f
	s_nop 0
	v_addc_co_u32_e32 v163, vcc, 0, v149, vcc
	global_store_dwordx4 v[162:163], v[130:133], off sc1
	v_cmp_lt_i32_e32 vcc, s18, v144
	s_mov_b32 s18, 0x4f000
	v_mov_b32_e32 v130, v34
	v_mov_b32_e32 v131, v24
	v_pk_mul_f32 v[130:131], v[130:131], v[150:151]
	v_mov_b32_e32 v133, v26
	v_sub_f32_e32 v132, v130, v131
	v_mov_b32_e32 v130, v35
	v_mov_b32_e32 v131, v25
	v_pk_mul_f32 v[130:131], v[130:131], v[152:153]
	s_nop 0
	v_sub_f32_e32 v130, v130, v131
	v_cvt_pk_bf16_f32 v130, v132, v130
	v_mov_b32_e32 v132, v36
	v_pk_mul_f32 v[132:133], v[132:133], v[160:161]
	s_nop 0
	v_sub_f32_e32 v131, v132, v133
	v_mov_b32_e32 v132, v37
	v_mov_b32_e32 v133, v27
	v_pk_mul_f32 v[132:133], v[132:133], v[154:155]
	s_nop 0
	v_sub_f32_e32 v132, v132, v133
	v_cvt_pk_bf16_f32 v131, v131, v132
	v_mov_b32_e32 v132, v24
	v_mov_b32_e32 v133, v34
	v_pk_mul_f32 v[132:133], v[132:133], v[150:151]
	v_mov_b32_e32 v150, v26
	v_add_f32_e32 v147, v133, v132
	v_mov_b32_e32 v132, v25
	v_mov_b32_e32 v133, v35
	v_mov_b32_e32 v151, v36
	v_pk_mul_f32 v[132:133], v[132:133], v[152:153]
	v_pk_mul_f32 v[150:151], v[150:151], v[160:161]
	v_add_f32_e32 v132, v133, v132
	v_add_f32_e32 v133, v151, v150
	v_mov_b32_e32 v150, v27
	v_mov_b32_e32 v151, v37
	v_pk_mul_f32 v[150:151], v[150:151], v[154:155]
	v_cvt_pk_bf16_f32 v132, v147, v132
	s_nop 0
	v_add_f32_e32 v147, v151, v150
	v_cvt_pk_bf16_f32 v133, v133, v147
	global_store_dwordx4 v[162:163], v[130:133], off offset:256 sc1
	v_mov_b32_e32 v162, v30
	v_mov_b32_e32 v163, v40
	s_waitcnt vmcnt(2)
	s_nop 1
	v_mov_b32_e32 v130, v232
	v_mov_b32_e32 v131, v233
	v_mov_b32_e32 v132, v234
	v_mov_b32_e32 v133, v235
	v_mov_b32_e32 v150, v236
	v_mov_b32_e32 v151, v237
	v_mov_b32_e32 v152, v238
	v_mov_b32_e32 v153, v239
	v_add_u32_e32 v248, 0xb0, v144
	v_lshrrev_b32_e32 v249, 6, v248
	v_cndmask_b32_e64 v248, v248, v249, s[40:41]
	v_lshlrev_b32_e32 v248, 5, v248
	v_and_b32_e32 v248, 0x7e0, v248
	v_add_lshl_u32 v248, v248, v145, 1
	v_ashrrev_i32_e32 v249, 31, v248
	v_lshl_add_u64 v[250:251], v[248:249], 2, s[20:21]
	global_load_dwordx4 v[232:235], v[250:251], off offset:16
	global_load_dwordx4 v[236:239], v[250:251], off
	s_nop 0
	v_cndmask_b32_e64 v161, v131, 0, vcc
	v_cndmask_b32_e64 v151, v151, 0, vcc
	v_cndmask_b32_e64 v150, v150, 1.0, vcc
	v_cndmask_b32_e64 v160, v130, 1.0, vcc
	v_mov_b32_e32 v130, v38
	v_mov_b32_e32 v131, v28
	v_pk_mul_f32 v[130:131], v[130:131], v[150:151]
	v_cndmask_b32_e64 v153, v153, 0, vcc
	v_cndmask_b32_e64 v152, v152, 1.0, vcc
	v_cndmask_b32_e64 v154, v132, 1.0, vcc
	v_sub_f32_e32 v132, v130, v131
	v_mov_b32_e32 v130, v39
	v_mov_b32_e32 v131, v29
	v_pk_mul_f32 v[130:131], v[130:131], v[152:153]
	v_cndmask_b32_e64 v155, v133, 0, vcc
	v_sub_f32_e32 v130, v130, v131
	v_cvt_pk_bf16_f32 v130, v132, v130
	v_mov_b32_e32 v132, v40
	v_mov_b32_e32 v133, v30
	v_pk_mul_f32 v[132:133], v[132:133], v[160:161]
	v_pk_mul_f32 v[162:163], v[162:163], v[160:161]
	v_sub_f32_e32 v131, v132, v133
	v_mov_b32_e32 v132, v41
	v_mov_b32_e32 v133, v31
	v_pk_mul_f32 v[132:133], v[132:133], v[154:155]
	s_nop 0
	v_sub_f32_e32 v132, v132, v133
	v_cvt_pk_bf16_f32 v131, v131, v132
	v_mov_b32_e32 v132, v28
	v_mov_b32_e32 v133, v38
	v_pk_mul_f32 v[132:133], v[132:133], v[150:151]
	s_nop 0
	v_add_f32_e32 v147, v133, v132
	v_mov_b32_e32 v132, v29
	v_mov_b32_e32 v133, v39
	v_pk_mul_f32 v[132:133], v[132:133], v[152:153]
	s_nop 0
	v_add_f32_e32 v132, v133, v132
	v_add_f32_e32 v133, v163, v162
	v_mov_b32_e32 v162, v31
	v_mov_b32_e32 v163, v41
	v_pk_mul_f32 v[162:163], v[162:163], v[154:155]
	v_cvt_pk_bf16_f32 v132, v147, v132
	s_nop 0
	v_add_f32_e32 v147, v163, v162
	v_add_co_u32_e32 v162, vcc, s18, v148
	v_cvt_pk_bf16_f32 v133, v133, v147
	s_movk_i32 s18, 0x3f4f
	s_nop 0
	v_addc_co_u32_e32 v163, vcc, 0, v149, vcc
	global_store_dwordx4 v[162:163], v[130:133], off sc1
	v_cmp_lt_i32_e32 vcc, s18, v144
	s_mov_b32 s18, 0x57000
	v_mov_b32_e32 v130, v16
	v_mov_b32_e32 v131, v8
	v_pk_mul_f32 v[130:131], v[130:131], v[150:151]
	v_mov_b32_e32 v133, v10
	v_sub_f32_e32 v132, v130, v131
	v_mov_b32_e32 v130, v17
	v_mov_b32_e32 v131, v9
	v_pk_mul_f32 v[130:131], v[130:131], v[152:153]
	s_nop 0
	v_sub_f32_e32 v130, v130, v131
	v_cvt_pk_bf16_f32 v130, v132, v130
	v_mov_b32_e32 v132, v18
	v_pk_mul_f32 v[132:133], v[132:133], v[160:161]
	s_nop 0
	v_sub_f32_e32 v131, v132, v133
	v_mov_b32_e32 v132, v19
	v_mov_b32_e32 v133, v11
	v_pk_mul_f32 v[132:133], v[132:133], v[154:155]
	s_nop 0
	v_sub_f32_e32 v132, v132, v133
	v_cvt_pk_bf16_f32 v131, v131, v132
	v_mov_b32_e32 v132, v8
	v_mov_b32_e32 v133, v16
	v_pk_mul_f32 v[132:133], v[132:133], v[150:151]
	v_mov_b32_e32 v150, v10
	v_add_f32_e32 v147, v133, v132
	v_mov_b32_e32 v132, v9
	v_mov_b32_e32 v133, v17
	v_mov_b32_e32 v151, v18
	v_pk_mul_f32 v[132:133], v[132:133], v[152:153]
	v_pk_mul_f32 v[150:151], v[150:151], v[160:161]
	v_add_f32_e32 v132, v133, v132
	v_add_f32_e32 v133, v151, v150
	v_mov_b32_e32 v150, v11
	v_mov_b32_e32 v151, v19
	v_pk_mul_f32 v[150:151], v[150:151], v[154:155]
	v_cvt_pk_bf16_f32 v132, v147, v132
	s_nop 0
	v_add_f32_e32 v147, v151, v150
	v_cvt_pk_bf16_f32 v133, v133, v147
	global_store_dwordx4 v[162:163], v[130:133], off offset:256 sc1
	v_mov_b32_e32 v162, v14
	v_mov_b32_e32 v163, v22
	s_waitcnt vmcnt(2)
; __device__ __forceinline__ unsigned cvt_pk_bf16(float lo, float hi) { unsigned r; asm volatile("v_cvt_pk_bf16_f32 %0, %1, %2" : "=v"(r) : "v"(lo), "v"(hi)); return r; }
;     template <int LDC> __device__ __forceinline__ void store_rope(const f32x4 (&acc)[2][2][4][2], bf16_t* base, int row0, int wc, int fq) const {
;     ...
;             for (int m = 0; m < 4; ++m) { const int row = row0 + ai * HALF + m * 16; bf16_t* rowp = rp + (size_t)(ai * HALF + m * 16) * LDC;
;                 const int t = row & (SEQ - 1), pos = axis ? (t & 63) : (t >> 6);
;                 f32x4 cs0 = *(const f32x4*)(TAB + (pos * 32 + f0) * 2), cs1 = *(const f32x4*)(TAB + (pos * 32 + f0) * 2 + 4);
;                 if (row >= ML) { cs0 = (f32x4){1.f, 0.f, 1.f, 0.f}; cs1 = cs0; }
; #pragma unroll
;                 for (int bj = 0; bj < 2; ++bj) { const f32x4 x1 = acc[ai][bj][m][0], x2 = acc[ai][bj][m][1];
;                     u32x4 w;
;                     w.x = cvt_pk_bf16(x1[0] * cs0[0] - x2[0] * cs0[1], x1[1] * cs0[2] - x2[1] * cs0[3]);
;                     w.y = cvt_pk_bf16(x1[2] * cs1[0] - x2[2] * cs1[1], x1[3] * cs1[2] - x2[3] * cs1[3]);
;                     w.z = cvt_pk_bf16(x2[0] * cs0[0] + x1[0] * cs0[1], x2[1] * cs0[2] + x1[1] * cs0[3]);
;                     w.w = cvt_pk_bf16(x2[2] * cs1[0] + x1[2] * cs1[1], x2[3] * cs1[2] + x1[3] * cs1[3]);
;                     *(u32x4*)(rowp + bj * HALF) = w; } }
	s_nop 1
	v_mov_b32_e32 v130, v232
	v_mov_b32_e32 v131, v233
	v_mov_b32_e32 v132, v234
	v_mov_b32_e32 v133, v235
	v_mov_b32_e32 v150, v236
	v_mov_b32_e32 v151, v237
	v_mov_b32_e32 v152, v238
	v_mov_b32_e32 v153, v239
	s_nop 0
	v_cndmask_b32_e64 v161, v131, 0, vcc
	v_cndmask_b32_e64 v151, v151, 0, vcc
	v_cndmask_b32_e64 v150, v150, 1.0, vcc
	v_cndmask_b32_e64 v160, v130, 1.0, vcc
	v_mov_b32_e32 v130, v20
	v_mov_b32_e32 v131, v12
	v_pk_mul_f32 v[130:131], v[130:131], v[150:151]
	v_cndmask_b32_e64 v153, v153, 0, vcc
	v_cndmask_b32_e64 v152, v152, 1.0, vcc
	v_cndmask_b32_e64 v154, v132, 1.0, vcc
	v_sub_f32_e32 v132, v130, v131
	v_mov_b32_e32 v130, v21
	v_mov_b32_e32 v131, v13
	v_pk_mul_f32 v[130:131], v[130:131], v[152:153]
	v_cndmask_b32_e64 v155, v133, 0, vcc
	v_sub_f32_e32 v130, v130, v131
	v_cvt_pk_bf16_f32 v130, v132, v130
	v_mov_b32_e32 v132, v22
	v_mov_b32_e32 v133, v14
	v_pk_mul_f32 v[132:133], v[132:133], v[160:161]
	v_pk_mul_f32 v[162:163], v[162:163], v[160:161]
	v_sub_f32_e32 v131, v132, v133
	v_mov_b32_e32 v132, v23
	v_mov_b32_e32 v133, v15
	v_pk_mul_f32 v[132:133], v[132:133], v[154:155]
	v_add_co_u32_e32 v148, vcc, s18, v148
	v_sub_f32_e32 v132, v132, v133
	v_cvt_pk_bf16_f32 v131, v131, v132
	v_mov_b32_e32 v132, v12
	v_mov_b32_e32 v133, v20
	v_pk_mul_f32 v[132:133], v[132:133], v[150:151]
	v_addc_co_u32_e32 v149, vcc, 0, v149, vcc
	v_add_f32_e32 v145, v133, v132
	v_mov_b32_e32 v132, v13
	v_mov_b32_e32 v133, v21
	v_pk_mul_f32 v[132:133], v[132:133], v[152:153]
	s_nop 0
	v_add_f32_e32 v132, v133, v132
	v_add_f32_e32 v133, v163, v162
	v_mov_b32_e32 v162, v15
	v_mov_b32_e32 v163, v23
	v_pk_mul_f32 v[162:163], v[162:163], v[154:155]
	v_cvt_pk_bf16_f32 v132, v145, v132
	s_nop 0
	v_add_f32_e32 v145, v163, v162
	v_cvt_pk_bf16_f32 v133, v133, v145
	global_store_dwordx4 v[148:149], v[130:133], off sc1
	s_nop 1
	v_mov_b32_e32 v130, v4
	v_mov_b32_e32 v131, v0
	v_pk_mul_f32 v[130:131], v[130:131], v[150:151]
	v_mov_b32_e32 v133, v2
	v_sub_f32_e32 v132, v130, v131
	v_mov_b32_e32 v130, v5
	v_mov_b32_e32 v131, v1
	v_pk_mul_f32 v[130:131], v[130:131], v[152:153]
	s_nop 0
	v_sub_f32_e32 v130, v130, v131
	v_cvt_pk_bf16_f32 v130, v132, v130
	v_mov_b32_e32 v132, v6
	v_pk_mul_f32 v[132:133], v[132:133], v[160:161]
	s_nop 0
	v_sub_f32_e32 v131, v132, v133
	v_mov_b32_e32 v132, v7
	v_mov_b32_e32 v133, v3
	v_pk_mul_f32 v[132:133], v[132:133], v[154:155]
	s_nop 0
	v_sub_f32_e32 v132, v132, v133
	v_cvt_pk_bf16_f32 v131, v131, v132
	v_mov_b32_e32 v132, v0
	v_mov_b32_e32 v133, v4
	v_pk_mul_f32 v[132:133], v[132:133], v[150:151]
	v_mov_b32_e32 v150, v2
	v_add_f32_e32 v145, v133, v132
	v_mov_b32_e32 v132, v1
	v_mov_b32_e32 v133, v5
	v_mov_b32_e32 v151, v6
	v_pk_mul_f32 v[132:133], v[132:133], v[152:153]
	v_pk_mul_f32 v[150:151], v[150:151], v[160:161]
	v_add_f32_e32 v132, v133, v132
	v_add_f32_e32 v133, v151, v150
	v_mov_b32_e32 v150, v3
	v_mov_b32_e32 v151, v7
	v_pk_mul_f32 v[150:151], v[150:151], v[154:155]
	v_cvt_pk_bf16_f32 v132, v145, v132
	s_nop 0
	v_add_f32_e32 v145, v151, v150
	v_cvt_pk_bf16_f32 v133, v133, v145
	global_store_dwordx4 v[148:149], v[130:133], off offset:256 sc1
